# RW scan: dead operand prefetch of each chunk's last step removed (as done for DN)
# speedup vs baseline: 1.0135x; 1.0135x over previous
.LBB0_859:
	v_readfirstlane_b32 s100, v92
	v_readfirstlane_b32 s101, v93
	s_sub_u32 s100, s100, m0
	s_subb_u32 s101, s101, 0
	s_waitcnt lgkmcnt(0)
	v_pk_fma_f32 v[106:107], v[84:85], v[34:35], 0 op_sel_hi:[1,1,0]
	v_pk_fma_f32 v[108:109], v[84:85], v[22:23], 0 op_sel_hi:[1,1,0]
	ds_read_b128 v[70:73], v100 offset:1568
	ds_read_b128 v[66:69], v100 offset:1584
	v_pk_fma_f32 v[106:107], v[86:87], v[36:37], v[106:107]
	v_pk_fma_f32 v[108:109], v[86:87], v[24:25], v[108:109]
	ds_read_b128 v[50:53], v100 offset:1824
	ds_read_b128 v[46:49], v100 offset:1840
	v_pk_fma_f32 v[106:107], v[88:89], v[38:39], v[106:107]
	v_pk_fma_f32 v[108:109], v[88:89], v[18:19], v[108:109]
	ds_read_b128 v[54:57], v100 offset:2080
	ds_read_b128 v[42:45], v100 offset:2096
	v_pk_fma_f32 v[106:107], v[90:91], v[40:41], v[106:107]
	v_pk_fma_f32 v[108:109], v[90:91], v[20:21], v[108:109]
	ds_read_b128 v[78:81], v100 offset:2336
	ds_read_b128 v[74:77], v100 offset:2352
	v_add_f32_e32 v130, v106, v107
	v_add_f32_e32 v131, v108, v109
	v_pk_mul_f32 v[114:115], v[84:85], v[2:3]
	v_add_f32_dpp v130, v130, v130 quad_perm:[1,0,3,2] row_mask:0xf bank_mask:0xf bound_ctrl:1
	v_add_f32_dpp v131, v131, v131 quad_perm:[1,0,3,2] row_mask:0xf bank_mask:0xf bound_ctrl:1
	v_pk_mul_f32 v[116:117], v[86:87], v[4:5]
	v_add_f32_dpp v130, v130, v130 quad_perm:[2,3,0,1] row_mask:0xf bank_mask:0xf bound_ctrl:1
	v_add_f32_dpp v131, v131, v131 quad_perm:[2,3,0,1] row_mask:0xf bank_mask:0xf bound_ctrl:1
	v_pk_mul_f32 v[118:119], v[88:89], v[6:7]
	v_add_f32_dpp v130, v130, v130 row_half_mirror row_mask:0xf bank_mask:0xf bound_ctrl:1
	v_add_f32_dpp v131, v131, v131 row_half_mirror row_mask:0xf bank_mask:0xf bound_ctrl:1
	v_pk_mul_f32 v[120:121], v[90:91], v[8:9]
	ds_read_b128 v[62:65], v100 offset:2592
	ds_read_b128 v[58:61], v100 offset:2608
	v_mul_f32_e32 v132, v130, v96
	v_mul_f32_e32 v133, v97, v94
	ds_read_b32 v0, v101 offset:2848
	v_add_f32_e32 v131, v132, v131
	ds_read_b64 v[98:99], v1 offset:3104
	v_add_f32_e32 v131, v133, v131
	v_pk_fma_f32 v[114:115], v[130:131], v[26:27], v[114:115] op_sel_hi:[0,1,1]
	v_pk_fma_f32 v[116:117], v[130:131], v[28:29], v[116:117] op_sel_hi:[0,1,1]
	v_cvt_pk_bf16_f32 v132, v131, v131
	v_pk_fma_f32 v[84:85], v[94:95], v[10:11], v[114:115] op_sel_hi:[0,1,1]
	global_store_short v144, v132, s[100:101]
	v_pk_fma_f32 v[118:119], v[130:131], v[30:31], v[118:119] op_sel_hi:[0,1,1]
	v_pk_fma_f32 v[86:87], v[94:95], v[12:13], v[116:117] op_sel_hi:[0,1,1]
	v_pk_fma_f32 v[120:121], v[130:131], v[32:33], v[120:121] op_sel_hi:[0,1,1]
	v_pk_fma_f32 v[88:89], v[94:95], v[14:15], v[118:119] op_sel_hi:[0,1,1]
	v_pk_fma_f32 v[90:91], v[94:95], v[16:17], v[120:121] op_sel_hi:[0,1,1]
	s_waitcnt lgkmcnt(0)
	v_pk_fma_f32 v[110:111], v[84:85], v[78:79], 0 op_sel_hi:[1,1,0]
	v_pk_fma_f32 v[112:113], v[84:85], v[70:71], 0 op_sel_hi:[1,1,0]
	ds_read_b128 v[22:25], v100 offset:3136
	ds_read_b128 v[18:21], v100 offset:3152
	v_pk_fma_f32 v[110:111], v[86:87], v[80:81], v[110:111]
	v_pk_fma_f32 v[112:113], v[86:87], v[72:73], v[112:113]
	ds_read_b128 v[2:5], v100 offset:3392
	ds_read_b128 v[6:9], v100 offset:3408
	v_pk_fma_f32 v[110:111], v[88:89], v[74:75], v[110:111]
	v_pk_fma_f32 v[112:113], v[88:89], v[66:67], v[112:113]
	ds_read_b128 v[10:13], v100 offset:3648
	ds_read_b128 v[14:17], v100 offset:3664
	v_pk_fma_f32 v[110:111], v[90:91], v[76:77], v[110:111]
	v_pk_fma_f32 v[112:113], v[90:91], v[68:69], v[112:113]
	ds_read_b128 v[34:37], v100 offset:3904
	ds_read_b128 v[38:41], v100 offset:3920
	v_add_f32_e32 v140, v110, v111
	v_add_f32_e32 v141, v112, v113
	v_pk_mul_f32 v[114:115], v[84:85], v[50:51]
	v_add_f32_dpp v140, v140, v140 quad_perm:[1,0,3,2] row_mask:0xf bank_mask:0xf bound_ctrl:1
	v_add_f32_dpp v141, v141, v141 quad_perm:[1,0,3,2] row_mask:0xf bank_mask:0xf bound_ctrl:1
	v_pk_mul_f32 v[116:117], v[86:87], v[52:53]
	v_add_f32_dpp v140, v140, v140 quad_perm:[2,3,0,1] row_mask:0xf bank_mask:0xf bound_ctrl:1
	v_add_f32_dpp v141, v141, v141 quad_perm:[2,3,0,1] row_mask:0xf bank_mask:0xf bound_ctrl:1
	v_pk_mul_f32 v[118:119], v[88:89], v[46:47]
	v_add_f32_dpp v140, v140, v140 row_half_mirror row_mask:0xf bank_mask:0xf bound_ctrl:1
	v_add_f32_dpp v141, v141, v141 row_half_mirror row_mask:0xf bank_mask:0xf bound_ctrl:1
	v_pk_mul_f32 v[120:121], v[90:91], v[48:49]
	ds_read_b128 v[26:29], v100 offset:4160
	ds_read_b128 v[30:33], v100 offset:4176
	v_mul_f32_e32 v142, v140, v98
	v_mul_f32_e32 v143, v99, v0
	ds_read_b32 v94, v101 offset:4416
	v_add_f32_e32 v141, v142, v141
	ds_read_b64 v[96:97], v1 offset:4672
	v_add_f32_e32 v141, v143, v141
	v_pk_fma_f32 v[114:115], v[140:141], v[62:63], v[114:115] op_sel_hi:[0,1,1]
	v_pk_fma_f32 v[116:117], v[140:141], v[64:65], v[116:117] op_sel_hi:[0,1,1]
	v_cvt_pk_bf16_f32 v142, v141, v141
	v_pk_fma_f32 v[84:85], v[0:1], v[54:55], v[114:115] op_sel_hi:[0,1,1]
	global_store_short v145, v142, s[100:101]
	v_pk_fma_f32 v[118:119], v[140:141], v[58:59], v[118:119] op_sel_hi:[0,1,1]
	v_pk_fma_f32 v[86:87], v[0:1], v[56:57], v[116:117] op_sel_hi:[0,1,1]
	v_pk_fma_f32 v[120:121], v[140:141], v[60:61], v[120:121] op_sel_hi:[0,1,1]
	v_pk_fma_f32 v[88:89], v[0:1], v[42:43], v[118:119] op_sel_hi:[0,1,1]
	v_pk_fma_f32 v[90:91], v[0:1], v[44:45], v[120:121] op_sel_hi:[0,1,1]
	s_waitcnt lgkmcnt(0)
	v_pk_fma_f32 v[106:107], v[84:85], v[34:35], 0 op_sel_hi:[1,1,0]
	v_pk_fma_f32 v[108:109], v[84:85], v[22:23], 0 op_sel_hi:[1,1,0]
	ds_read_b128 v[70:73], v100 offset:4704
	ds_read_b128 v[66:69], v100 offset:4720
	v_pk_fma_f32 v[106:107], v[86:87], v[36:37], v[106:107]
	v_pk_fma_f32 v[108:109], v[86:87], v[24:25], v[108:109]
	ds_read_b128 v[50:53], v100 offset:4960
	ds_read_b128 v[46:49], v100 offset:4976
	v_pk_fma_f32 v[106:107], v[88:89], v[38:39], v[106:107]
	v_pk_fma_f32 v[108:109], v[88:89], v[18:19], v[108:109]
	ds_read_b128 v[54:57], v100 offset:5216
	ds_read_b128 v[42:45], v100 offset:5232
	v_pk_fma_f32 v[106:107], v[90:91], v[40:41], v[106:107]
	v_pk_fma_f32 v[108:109], v[90:91], v[20:21], v[108:109]
	ds_read_b128 v[78:81], v100 offset:5472
	ds_read_b128 v[74:77], v100 offset:5488
	v_add_f32_e32 v130, v106, v107
	v_add_f32_e32 v131, v108, v109
	v_pk_mul_f32 v[114:115], v[84:85], v[2:3]
	v_add_f32_dpp v130, v130, v130 quad_perm:[1,0,3,2] row_mask:0xf bank_mask:0xf bound_ctrl:1
	v_add_f32_dpp v131, v131, v131 quad_perm:[1,0,3,2] row_mask:0xf bank_mask:0xf bound_ctrl:1
	v_pk_mul_f32 v[116:117], v[86:87], v[4:5]
	v_add_f32_dpp v130, v130, v130 quad_perm:[2,3,0,1] row_mask:0xf bank_mask:0xf bound_ctrl:1
	v_add_f32_dpp v131, v131, v131 quad_perm:[2,3,0,1] row_mask:0xf bank_mask:0xf bound_ctrl:1
	v_pk_mul_f32 v[118:119], v[88:89], v[6:7]
	v_add_f32_dpp v130, v130, v130 row_half_mirror row_mask:0xf bank_mask:0xf bound_ctrl:1
	v_add_f32_dpp v131, v131, v131 row_half_mirror row_mask:0xf bank_mask:0xf bound_ctrl:1
	v_pk_mul_f32 v[120:121], v[90:91], v[8:9]
	ds_read_b128 v[62:65], v100 offset:5728
	ds_read_b128 v[58:61], v100 offset:5744
	v_mul_f32_e32 v132, v130, v96
	v_mul_f32_e32 v133, v97, v94
	ds_read_b32 v0, v101 offset:5984
	v_add_f32_e32 v131, v132, v131
	ds_read_b64 v[98:99], v1 offset:6240
	v_add_f32_e32 v131, v133, v131
	v_pk_fma_f32 v[114:115], v[130:131], v[26:27], v[114:115] op_sel_hi:[0,1,1]
	v_pk_fma_f32 v[116:117], v[130:131], v[28:29], v[116:117] op_sel_hi:[0,1,1]
	v_cvt_pk_bf16_f32 v132, v131, v131
	v_pk_fma_f32 v[84:85], v[94:95], v[10:11], v[114:115] op_sel_hi:[0,1,1]
	global_store_short v146, v132, s[100:101]
	v_pk_fma_f32 v[118:119], v[130:131], v[30:31], v[118:119] op_sel_hi:[0,1,1]
	v_pk_fma_f32 v[86:87], v[94:95], v[12:13], v[116:117] op_sel_hi:[0,1,1]
	v_pk_fma_f32 v[120:121], v[130:131], v[32:33], v[120:121] op_sel_hi:[0,1,1]
	v_pk_fma_f32 v[88:89], v[94:95], v[14:15], v[118:119] op_sel_hi:[0,1,1]
	v_pk_fma_f32 v[90:91], v[94:95], v[16:17], v[120:121] op_sel_hi:[0,1,1]
	s_waitcnt lgkmcnt(0)
	v_pk_fma_f32 v[110:111], v[84:85], v[78:79], 0 op_sel_hi:[1,1,0]
	v_pk_fma_f32 v[112:113], v[84:85], v[70:71], 0 op_sel_hi:[1,1,0]
	ds_read_b128 v[22:25], v100 offset:6272
	ds_read_b128 v[18:21], v100 offset:6288
	v_pk_fma_f32 v[110:111], v[86:87], v[80:81], v[110:111]
	v_pk_fma_f32 v[112:113], v[86:87], v[72:73], v[112:113]
	ds_read_b128 v[2:5], v100 offset:6528
	ds_read_b128 v[6:9], v100 offset:6544
	v_pk_fma_f32 v[110:111], v[88:89], v[74:75], v[110:111]
	v_pk_fma_f32 v[112:113], v[88:89], v[66:67], v[112:113]
	ds_read_b128 v[10:13], v100 offset:6784
	ds_read_b128 v[14:17], v100 offset:6800
	v_pk_fma_f32 v[110:111], v[90:91], v[76:77], v[110:111]
	v_pk_fma_f32 v[112:113], v[90:91], v[68:69], v[112:113]
	ds_read_b128 v[34:37], v100 offset:7040
	ds_read_b128 v[38:41], v100 offset:7056
	v_add_f32_e32 v140, v110, v111
	v_add_f32_e32 v141, v112, v113
	v_pk_mul_f32 v[114:115], v[84:85], v[50:51]
	v_add_f32_dpp v140, v140, v140 quad_perm:[1,0,3,2] row_mask:0xf bank_mask:0xf bound_ctrl:1
	v_add_f32_dpp v141, v141, v141 quad_perm:[1,0,3,2] row_mask:0xf bank_mask:0xf bound_ctrl:1
	v_pk_mul_f32 v[116:117], v[86:87], v[52:53]
	v_add_f32_dpp v140, v140, v140 quad_perm:[2,3,0,1] row_mask:0xf bank_mask:0xf bound_ctrl:1
	v_add_f32_dpp v141, v141, v141 quad_perm:[2,3,0,1] row_mask:0xf bank_mask:0xf bound_ctrl:1
	v_pk_mul_f32 v[118:119], v[88:89], v[46:47]
	v_add_f32_dpp v140, v140, v140 row_half_mirror row_mask:0xf bank_mask:0xf bound_ctrl:1
	v_add_f32_dpp v141, v141, v141 row_half_mirror row_mask:0xf bank_mask:0xf bound_ctrl:1
	v_pk_mul_f32 v[120:121], v[90:91], v[48:49]
	ds_read_b128 v[26:29], v100 offset:7296
	ds_read_b128 v[30:33], v100 offset:7312
	v_mul_f32_e32 v142, v140, v98
	v_mul_f32_e32 v143, v99, v0
	ds_read_b32 v94, v101 offset:7552
	v_add_f32_e32 v141, v142, v141
	ds_read_b64 v[96:97], v1 offset:7808
	v_add_f32_e32 v141, v143, v141
	v_pk_fma_f32 v[114:115], v[140:141], v[62:63], v[114:115] op_sel_hi:[0,1,1]
	v_pk_fma_f32 v[116:117], v[140:141], v[64:65], v[116:117] op_sel_hi:[0,1,1]
	v_cvt_pk_bf16_f32 v142, v141, v141
	v_pk_fma_f32 v[84:85], v[0:1], v[54:55], v[114:115] op_sel_hi:[0,1,1]
	global_store_short v147, v142, s[100:101]
	v_pk_fma_f32 v[118:119], v[140:141], v[58:59], v[118:119] op_sel_hi:[0,1,1]
	v_pk_fma_f32 v[86:87], v[0:1], v[56:57], v[116:117] op_sel_hi:[0,1,1]
	v_pk_fma_f32 v[120:121], v[140:141], v[60:61], v[120:121] op_sel_hi:[0,1,1]
	v_pk_fma_f32 v[88:89], v[0:1], v[42:43], v[118:119] op_sel_hi:[0,1,1]
	v_pk_fma_f32 v[90:91], v[0:1], v[44:45], v[120:121] op_sel_hi:[0,1,1]
	s_waitcnt lgkmcnt(0)
	v_pk_fma_f32 v[106:107], v[84:85], v[34:35], 0 op_sel_hi:[1,1,0]
	v_pk_fma_f32 v[108:109], v[84:85], v[22:23], 0 op_sel_hi:[1,1,0]
	ds_read_b128 v[70:73], v100 offset:7840
	ds_read_b128 v[66:69], v100 offset:7856
	v_pk_fma_f32 v[106:107], v[86:87], v[36:37], v[106:107]
	v_pk_fma_f32 v[108:109], v[86:87], v[24:25], v[108:109]
	ds_read_b128 v[50:53], v100 offset:8096
	ds_read_b128 v[46:49], v100 offset:8112
	v_pk_fma_f32 v[106:107], v[88:89], v[38:39], v[106:107]
	v_pk_fma_f32 v[108:109], v[88:89], v[18:19], v[108:109]
	ds_read_b128 v[54:57], v100 offset:8352
	ds_read_b128 v[42:45], v100 offset:8368
	v_pk_fma_f32 v[106:107], v[90:91], v[40:41], v[106:107]
	v_pk_fma_f32 v[108:109], v[90:91], v[20:21], v[108:109]
	ds_read_b128 v[78:81], v100 offset:8608
	ds_read_b128 v[74:77], v100 offset:8624
	v_add_f32_e32 v130, v106, v107
	v_add_f32_e32 v131, v108, v109
	v_pk_mul_f32 v[114:115], v[84:85], v[2:3]
	v_add_f32_dpp v130, v130, v130 quad_perm:[1,0,3,2] row_mask:0xf bank_mask:0xf bound_ctrl:1
	v_add_f32_dpp v131, v131, v131 quad_perm:[1,0,3,2] row_mask:0xf bank_mask:0xf bound_ctrl:1
	v_pk_mul_f32 v[116:117], v[86:87], v[4:5]
	v_add_f32_dpp v130, v130, v130 quad_perm:[2,3,0,1] row_mask:0xf bank_mask:0xf bound_ctrl:1
	v_add_f32_dpp v131, v131, v131 quad_perm:[2,3,0,1] row_mask:0xf bank_mask:0xf bound_ctrl:1
	v_pk_mul_f32 v[118:119], v[88:89], v[6:7]
	v_add_f32_dpp v130, v130, v130 row_half_mirror row_mask:0xf bank_mask:0xf bound_ctrl:1
	v_add_f32_dpp v131, v131, v131 row_half_mirror row_mask:0xf bank_mask:0xf bound_ctrl:1
	v_pk_mul_f32 v[120:121], v[90:91], v[8:9]
	ds_read_b128 v[62:65], v100 offset:8864
	ds_read_b128 v[58:61], v100 offset:8880
	v_mul_f32_e32 v132, v130, v96
	v_mul_f32_e32 v133, v97, v94
	ds_read_b32 v0, v101 offset:9120
	v_add_f32_e32 v131, v132, v131
	ds_read_b64 v[98:99], v1 offset:9376
	v_add_f32_e32 v131, v133, v131
	v_pk_fma_f32 v[114:115], v[130:131], v[26:27], v[114:115] op_sel_hi:[0,1,1]
	v_pk_fma_f32 v[116:117], v[130:131], v[28:29], v[116:117] op_sel_hi:[0,1,1]
	v_cvt_pk_bf16_f32 v132, v131, v131
	v_pk_fma_f32 v[84:85], v[94:95], v[10:11], v[114:115] op_sel_hi:[0,1,1]
	global_store_short v148, v132, s[100:101]
	v_pk_fma_f32 v[118:119], v[130:131], v[30:31], v[118:119] op_sel_hi:[0,1,1]
	v_pk_fma_f32 v[86:87], v[94:95], v[12:13], v[116:117] op_sel_hi:[0,1,1]
	v_pk_fma_f32 v[120:121], v[130:131], v[32:33], v[120:121] op_sel_hi:[0,1,1]
	v_pk_fma_f32 v[88:89], v[94:95], v[14:15], v[118:119] op_sel_hi:[0,1,1]
	v_pk_fma_f32 v[90:91], v[94:95], v[16:17], v[120:121] op_sel_hi:[0,1,1]
	s_waitcnt lgkmcnt(0)
	v_pk_fma_f32 v[110:111], v[84:85], v[78:79], 0 op_sel_hi:[1,1,0]
	v_pk_fma_f32 v[112:113], v[84:85], v[70:71], 0 op_sel_hi:[1,1,0]
	ds_read_b128 v[22:25], v100 offset:9408
	ds_read_b128 v[18:21], v100 offset:9424
	v_pk_fma_f32 v[110:111], v[86:87], v[80:81], v[110:111]
	v_pk_fma_f32 v[112:113], v[86:87], v[72:73], v[112:113]
	ds_read_b128 v[2:5], v100 offset:9664
	ds_read_b128 v[6:9], v100 offset:9680
	v_pk_fma_f32 v[110:111], v[88:89], v[74:75], v[110:111]
	v_pk_fma_f32 v[112:113], v[88:89], v[66:67], v[112:113]
	ds_read_b128 v[10:13], v100 offset:9920
	ds_read_b128 v[14:17], v100 offset:9936
	v_pk_fma_f32 v[110:111], v[90:91], v[76:77], v[110:111]
	v_pk_fma_f32 v[112:113], v[90:91], v[68:69], v[112:113]
	ds_read_b128 v[34:37], v100 offset:10176
	ds_read_b128 v[38:41], v100 offset:10192
	v_add_f32_e32 v140, v110, v111
	v_add_f32_e32 v141, v112, v113
	v_pk_mul_f32 v[114:115], v[84:85], v[50:51]
	v_add_f32_dpp v140, v140, v140 quad_perm:[1,0,3,2] row_mask:0xf bank_mask:0xf bound_ctrl:1
	v_add_f32_dpp v141, v141, v141 quad_perm:[1,0,3,2] row_mask:0xf bank_mask:0xf bound_ctrl:1
	v_pk_mul_f32 v[116:117], v[86:87], v[52:53]
	v_add_f32_dpp v140, v140, v140 quad_perm:[2,3,0,1] row_mask:0xf bank_mask:0xf bound_ctrl:1
	v_add_f32_dpp v141, v141, v141 quad_perm:[2,3,0,1] row_mask:0xf bank_mask:0xf bound_ctrl:1
	v_pk_mul_f32 v[118:119], v[88:89], v[46:47]
	v_add_f32_dpp v140, v140, v140 row_half_mirror row_mask:0xf bank_mask:0xf bound_ctrl:1
	v_add_f32_dpp v141, v141, v141 row_half_mirror row_mask:0xf bank_mask:0xf bound_ctrl:1
	v_pk_mul_f32 v[120:121], v[90:91], v[48:49]
	ds_read_b128 v[26:29], v100 offset:10432
	ds_read_b128 v[30:33], v100 offset:10448
	v_mul_f32_e32 v142, v140, v98
	v_mul_f32_e32 v143, v99, v0
	ds_read_b32 v94, v101 offset:10688
	v_add_f32_e32 v141, v142, v141
	ds_read_b64 v[96:97], v1 offset:10944
	v_add_f32_e32 v141, v143, v141
	v_pk_fma_f32 v[114:115], v[140:141], v[62:63], v[114:115] op_sel_hi:[0,1,1]
	v_pk_fma_f32 v[116:117], v[140:141], v[64:65], v[116:117] op_sel_hi:[0,1,1]
	v_cvt_pk_bf16_f32 v142, v141, v141
	v_pk_fma_f32 v[84:85], v[0:1], v[54:55], v[114:115] op_sel_hi:[0,1,1]
	global_store_short v149, v142, s[100:101]
	v_pk_fma_f32 v[118:119], v[140:141], v[58:59], v[118:119] op_sel_hi:[0,1,1]
	v_pk_fma_f32 v[86:87], v[0:1], v[56:57], v[116:117] op_sel_hi:[0,1,1]
	v_pk_fma_f32 v[120:121], v[140:141], v[60:61], v[120:121] op_sel_hi:[0,1,1]
	v_pk_fma_f32 v[88:89], v[0:1], v[42:43], v[118:119] op_sel_hi:[0,1,1]
	v_pk_fma_f32 v[90:91], v[0:1], v[44:45], v[120:121] op_sel_hi:[0,1,1]
	s_waitcnt lgkmcnt(0)
	v_pk_fma_f32 v[106:107], v[84:85], v[34:35], 0 op_sel_hi:[1,1,0]
	v_pk_fma_f32 v[108:109], v[84:85], v[22:23], 0 op_sel_hi:[1,1,0]
	ds_read_b128 v[70:73], v100 offset:10976
	ds_read_b128 v[66:69], v100 offset:10992
	v_pk_fma_f32 v[106:107], v[86:87], v[36:37], v[106:107]
	v_pk_fma_f32 v[108:109], v[86:87], v[24:25], v[108:109]
	ds_read_b128 v[50:53], v100 offset:11232
	ds_read_b128 v[46:49], v100 offset:11248
	v_pk_fma_f32 v[106:107], v[88:89], v[38:39], v[106:107]
	v_pk_fma_f32 v[108:109], v[88:89], v[18:19], v[108:109]
	ds_read_b128 v[54:57], v100 offset:11488
	ds_read_b128 v[42:45], v100 offset:11504
	v_pk_fma_f32 v[106:107], v[90:91], v[40:41], v[106:107]
	v_pk_fma_f32 v[108:109], v[90:91], v[20:21], v[108:109]
	ds_read_b128 v[78:81], v100 offset:11744
	ds_read_b128 v[74:77], v100 offset:11760
	v_add_f32_e32 v130, v106, v107
	v_add_f32_e32 v131, v108, v109
	v_pk_mul_f32 v[114:115], v[84:85], v[2:3]
	v_add_f32_dpp v130, v130, v130 quad_perm:[1,0,3,2] row_mask:0xf bank_mask:0xf bound_ctrl:1
	v_add_f32_dpp v131, v131, v131 quad_perm:[1,0,3,2] row_mask:0xf bank_mask:0xf bound_ctrl:1
	v_pk_mul_f32 v[116:117], v[86:87], v[4:5]
	v_add_f32_dpp v130, v130, v130 quad_perm:[2,3,0,1] row_mask:0xf bank_mask:0xf bound_ctrl:1
	v_add_f32_dpp v131, v131, v131 quad_perm:[2,3,0,1] row_mask:0xf bank_mask:0xf bound_ctrl:1
	v_pk_mul_f32 v[118:119], v[88:89], v[6:7]
	v_add_f32_dpp v130, v130, v130 row_half_mirror row_mask:0xf bank_mask:0xf bound_ctrl:1
	v_add_f32_dpp v131, v131, v131 row_half_mirror row_mask:0xf bank_mask:0xf bound_ctrl:1
	v_pk_mul_f32 v[120:121], v[90:91], v[8:9]
	ds_read_b128 v[62:65], v100 offset:12000
	ds_read_b128 v[58:61], v100 offset:12016
	v_mul_f32_e32 v132, v130, v96
	v_mul_f32_e32 v133, v97, v94
	ds_read_b32 v0, v101 offset:12256
	v_add_f32_e32 v131, v132, v131
	ds_read_b64 v[98:99], v1 offset:12512
	v_add_f32_e32 v131, v133, v131
	v_pk_fma_f32 v[114:115], v[130:131], v[26:27], v[114:115] op_sel_hi:[0,1,1]
	v_pk_fma_f32 v[116:117], v[130:131], v[28:29], v[116:117] op_sel_hi:[0,1,1]
	v_cvt_pk_bf16_f32 v132, v131, v131
	v_pk_fma_f32 v[84:85], v[94:95], v[10:11], v[114:115] op_sel_hi:[0,1,1]
	global_store_short v150, v132, s[100:101]
	v_pk_fma_f32 v[118:119], v[130:131], v[30:31], v[118:119] op_sel_hi:[0,1,1]
	v_pk_fma_f32 v[86:87], v[94:95], v[12:13], v[116:117] op_sel_hi:[0,1,1]
	v_pk_fma_f32 v[120:121], v[130:131], v[32:33], v[120:121] op_sel_hi:[0,1,1]
	v_pk_fma_f32 v[88:89], v[94:95], v[14:15], v[118:119] op_sel_hi:[0,1,1]
	v_pk_fma_f32 v[90:91], v[94:95], v[16:17], v[120:121] op_sel_hi:[0,1,1]
	s_waitcnt lgkmcnt(0)
	v_pk_fma_f32 v[110:111], v[84:85], v[78:79], 0 op_sel_hi:[1,1,0]
	v_pk_fma_f32 v[112:113], v[84:85], v[70:71], 0 op_sel_hi:[1,1,0]
	ds_read_b128 v[22:25], v100 offset:12544
	ds_read_b128 v[18:21], v100 offset:12560
	v_pk_fma_f32 v[110:111], v[86:87], v[80:81], v[110:111]
	v_pk_fma_f32 v[112:113], v[86:87], v[72:73], v[112:113]
	ds_read_b128 v[2:5], v100 offset:12800
	ds_read_b128 v[6:9], v100 offset:12816
	v_pk_fma_f32 v[110:111], v[88:89], v[74:75], v[110:111]
	v_pk_fma_f32 v[112:113], v[88:89], v[66:67], v[112:113]
	ds_read_b128 v[10:13], v100 offset:13056
	ds_read_b128 v[14:17], v100 offset:13072
	v_pk_fma_f32 v[110:111], v[90:91], v[76:77], v[110:111]
	v_pk_fma_f32 v[112:113], v[90:91], v[68:69], v[112:113]
	ds_read_b128 v[34:37], v100 offset:13312
	ds_read_b128 v[38:41], v100 offset:13328
	v_add_f32_e32 v140, v110, v111
	v_add_f32_e32 v141, v112, v113
	v_pk_mul_f32 v[114:115], v[84:85], v[50:51]
	v_add_f32_dpp v140, v140, v140 quad_perm:[1,0,3,2] row_mask:0xf bank_mask:0xf bound_ctrl:1
	v_add_f32_dpp v141, v141, v141 quad_perm:[1,0,3,2] row_mask:0xf bank_mask:0xf bound_ctrl:1
	v_pk_mul_f32 v[116:117], v[86:87], v[52:53]
	v_add_f32_dpp v140, v140, v140 quad_perm:[2,3,0,1] row_mask:0xf bank_mask:0xf bound_ctrl:1
	v_add_f32_dpp v141, v141, v141 quad_perm:[2,3,0,1] row_mask:0xf bank_mask:0xf bound_ctrl:1
	v_pk_mul_f32 v[118:119], v[88:89], v[46:47]
	v_add_f32_dpp v140, v140, v140 row_half_mirror row_mask:0xf bank_mask:0xf bound_ctrl:1
	v_add_f32_dpp v141, v141, v141 row_half_mirror row_mask:0xf bank_mask:0xf bound_ctrl:1
	v_pk_mul_f32 v[120:121], v[90:91], v[48:49]
	ds_read_b128 v[26:29], v100 offset:13568
	ds_read_b128 v[30:33], v100 offset:13584
	v_mul_f32_e32 v142, v140, v98
	v_mul_f32_e32 v143, v99, v0
	ds_read_b32 v94, v101 offset:13824
	v_add_f32_e32 v141, v142, v141
	ds_read_b64 v[96:97], v1 offset:14080
	v_add_f32_e32 v141, v143, v141
	v_pk_fma_f32 v[114:115], v[140:141], v[62:63], v[114:115] op_sel_hi:[0,1,1]
	v_pk_fma_f32 v[116:117], v[140:141], v[64:65], v[116:117] op_sel_hi:[0,1,1]
	v_cvt_pk_bf16_f32 v142, v141, v141
	v_pk_fma_f32 v[84:85], v[0:1], v[54:55], v[114:115] op_sel_hi:[0,1,1]
	global_store_short v151, v142, s[100:101]
	v_pk_fma_f32 v[118:119], v[140:141], v[58:59], v[118:119] op_sel_hi:[0,1,1]
	v_pk_fma_f32 v[86:87], v[0:1], v[56:57], v[116:117] op_sel_hi:[0,1,1]
	v_pk_fma_f32 v[120:121], v[140:141], v[60:61], v[120:121] op_sel_hi:[0,1,1]
	v_pk_fma_f32 v[88:89], v[0:1], v[42:43], v[118:119] op_sel_hi:[0,1,1]
	v_pk_fma_f32 v[90:91], v[0:1], v[44:45], v[120:121] op_sel_hi:[0,1,1]
	s_waitcnt lgkmcnt(0)
	v_pk_fma_f32 v[106:107], v[84:85], v[34:35], 0 op_sel_hi:[1,1,0]
	v_pk_fma_f32 v[108:109], v[84:85], v[22:23], 0 op_sel_hi:[1,1,0]
	ds_read_b128 v[70:73], v100 offset:14112
	ds_read_b128 v[66:69], v100 offset:14128
	v_pk_fma_f32 v[106:107], v[86:87], v[36:37], v[106:107]
	v_pk_fma_f32 v[108:109], v[86:87], v[24:25], v[108:109]
	ds_read_b128 v[50:53], v100 offset:14368
	ds_read_b128 v[46:49], v100 offset:14384
	v_pk_fma_f32 v[106:107], v[88:89], v[38:39], v[106:107]
	v_pk_fma_f32 v[108:109], v[88:89], v[18:19], v[108:109]
	ds_read_b128 v[54:57], v100 offset:14624
	ds_read_b128 v[42:45], v100 offset:14640
	v_pk_fma_f32 v[106:107], v[90:91], v[40:41], v[106:107]
	v_pk_fma_f32 v[108:109], v[90:91], v[20:21], v[108:109]
	ds_read_b128 v[78:81], v100 offset:14880
	ds_read_b128 v[74:77], v100 offset:14896
	v_add_f32_e32 v130, v106, v107
	v_add_f32_e32 v131, v108, v109
	v_pk_mul_f32 v[114:115], v[84:85], v[2:3]
	v_add_f32_dpp v130, v130, v130 quad_perm:[1,0,3,2] row_mask:0xf bank_mask:0xf bound_ctrl:1
	v_add_f32_dpp v131, v131, v131 quad_perm:[1,0,3,2] row_mask:0xf bank_mask:0xf bound_ctrl:1
	v_pk_mul_f32 v[116:117], v[86:87], v[4:5]
	v_add_f32_dpp v130, v130, v130 quad_perm:[2,3,0,1] row_mask:0xf bank_mask:0xf bound_ctrl:1
	v_add_f32_dpp v131, v131, v131 quad_perm:[2,3,0,1] row_mask:0xf bank_mask:0xf bound_ctrl:1
	v_pk_mul_f32 v[118:119], v[88:89], v[6:7]
	v_add_f32_dpp v130, v130, v130 row_half_mirror row_mask:0xf bank_mask:0xf bound_ctrl:1
	v_add_f32_dpp v131, v131, v131 row_half_mirror row_mask:0xf bank_mask:0xf bound_ctrl:1
	v_pk_mul_f32 v[120:121], v[90:91], v[8:9]
	ds_read_b128 v[62:65], v100 offset:15136
	ds_read_b128 v[58:61], v100 offset:15152
	v_mul_f32_e32 v132, v130, v96
	v_mul_f32_e32 v133, v97, v94
	ds_read_b32 v0, v101 offset:15392
	v_add_f32_e32 v131, v132, v131
	ds_read_b64 v[98:99], v1 offset:15648
	v_add_f32_e32 v131, v133, v131
	v_pk_fma_f32 v[114:115], v[130:131], v[26:27], v[114:115] op_sel_hi:[0,1,1]
	v_pk_fma_f32 v[116:117], v[130:131], v[28:29], v[116:117] op_sel_hi:[0,1,1]
	v_cvt_pk_bf16_f32 v132, v131, v131
	v_pk_fma_f32 v[84:85], v[94:95], v[10:11], v[114:115] op_sel_hi:[0,1,1]
	global_store_short v152, v132, s[100:101]
	v_pk_fma_f32 v[118:119], v[130:131], v[30:31], v[118:119] op_sel_hi:[0,1,1]
	v_pk_fma_f32 v[86:87], v[94:95], v[12:13], v[116:117] op_sel_hi:[0,1,1]
	v_pk_fma_f32 v[120:121], v[130:131], v[32:33], v[120:121] op_sel_hi:[0,1,1]
	v_pk_fma_f32 v[88:89], v[94:95], v[14:15], v[118:119] op_sel_hi:[0,1,1]
	v_pk_fma_f32 v[90:91], v[94:95], v[16:17], v[120:121] op_sel_hi:[0,1,1]
	s_waitcnt lgkmcnt(0)
	v_pk_fma_f32 v[110:111], v[84:85], v[78:79], 0 op_sel_hi:[1,1,0]
	v_pk_fma_f32 v[112:113], v[84:85], v[70:71], 0 op_sel_hi:[1,1,0]
	ds_read_b128 v[22:25], v100 offset:15680
	ds_read_b128 v[18:21], v100 offset:15696
	v_pk_fma_f32 v[110:111], v[86:87], v[80:81], v[110:111]
	v_pk_fma_f32 v[112:113], v[86:87], v[72:73], v[112:113]
	ds_read_b128 v[2:5], v100 offset:15936
	ds_read_b128 v[6:9], v100 offset:15952
	v_pk_fma_f32 v[110:111], v[88:89], v[74:75], v[110:111]
	v_pk_fma_f32 v[112:113], v[88:89], v[66:67], v[112:113]
	ds_read_b128 v[10:13], v100 offset:16192
	ds_read_b128 v[14:17], v100 offset:16208
	v_pk_fma_f32 v[110:111], v[90:91], v[76:77], v[110:111]
	v_pk_fma_f32 v[112:113], v[90:91], v[68:69], v[112:113]
	ds_read_b128 v[34:37], v100 offset:16448
	ds_read_b128 v[38:41], v100 offset:16464
	v_add_f32_e32 v140, v110, v111
	v_add_f32_e32 v141, v112, v113
	v_pk_mul_f32 v[114:115], v[84:85], v[50:51]
	v_add_f32_dpp v140, v140, v140 quad_perm:[1,0,3,2] row_mask:0xf bank_mask:0xf bound_ctrl:1
	v_add_f32_dpp v141, v141, v141 quad_perm:[1,0,3,2] row_mask:0xf bank_mask:0xf bound_ctrl:1
	v_pk_mul_f32 v[116:117], v[86:87], v[52:53]
	v_add_f32_dpp v140, v140, v140 quad_perm:[2,3,0,1] row_mask:0xf bank_mask:0xf bound_ctrl:1
	v_add_f32_dpp v141, v141, v141 quad_perm:[2,3,0,1] row_mask:0xf bank_mask:0xf bound_ctrl:1
	v_pk_mul_f32 v[118:119], v[88:89], v[46:47]
	v_add_f32_dpp v140, v140, v140 row_half_mirror row_mask:0xf bank_mask:0xf bound_ctrl:1
	v_add_f32_dpp v141, v141, v141 row_half_mirror row_mask:0xf bank_mask:0xf bound_ctrl:1
	v_pk_mul_f32 v[120:121], v[90:91], v[48:49]
	ds_read_b128 v[26:29], v100 offset:16704
	ds_read_b128 v[30:33], v100 offset:16720
	v_mul_f32_e32 v142, v140, v98
	v_mul_f32_e32 v143, v99, v0
	ds_read_b32 v94, v101 offset:16960
	v_add_f32_e32 v141, v142, v141
	ds_read_b64 v[96:97], v1 offset:17216
	v_add_f32_e32 v141, v143, v141
	v_pk_fma_f32 v[114:115], v[140:141], v[62:63], v[114:115] op_sel_hi:[0,1,1]
	v_pk_fma_f32 v[116:117], v[140:141], v[64:65], v[116:117] op_sel_hi:[0,1,1]
	v_cvt_pk_bf16_f32 v142, v141, v141
	v_pk_fma_f32 v[84:85], v[0:1], v[54:55], v[114:115] op_sel_hi:[0,1,1]
	global_store_short v153, v142, s[100:101]
	v_pk_fma_f32 v[118:119], v[140:141], v[58:59], v[118:119] op_sel_hi:[0,1,1]
	v_pk_fma_f32 v[86:87], v[0:1], v[56:57], v[116:117] op_sel_hi:[0,1,1]
	v_pk_fma_f32 v[120:121], v[140:141], v[60:61], v[120:121] op_sel_hi:[0,1,1]
	v_pk_fma_f32 v[88:89], v[0:1], v[42:43], v[118:119] op_sel_hi:[0,1,1]
	v_pk_fma_f32 v[90:91], v[0:1], v[44:45], v[120:121] op_sel_hi:[0,1,1]
	s_waitcnt lgkmcnt(0)
	v_pk_fma_f32 v[106:107], v[84:85], v[34:35], 0 op_sel_hi:[1,1,0]
	v_pk_fma_f32 v[108:109], v[84:85], v[22:23], 0 op_sel_hi:[1,1,0]
	ds_read_b128 v[70:73], v100 offset:17248
	ds_read_b128 v[66:69], v100 offset:17264
	v_pk_fma_f32 v[106:107], v[86:87], v[36:37], v[106:107]
	v_pk_fma_f32 v[108:109], v[86:87], v[24:25], v[108:109]
	ds_read_b128 v[50:53], v100 offset:17504
	ds_read_b128 v[46:49], v100 offset:17520
	v_pk_fma_f32 v[106:107], v[88:89], v[38:39], v[106:107]
	v_pk_fma_f32 v[108:109], v[88:89], v[18:19], v[108:109]
	ds_read_b128 v[54:57], v100 offset:17760
	ds_read_b128 v[42:45], v100 offset:17776
	v_pk_fma_f32 v[106:107], v[90:91], v[40:41], v[106:107]
	v_pk_fma_f32 v[108:109], v[90:91], v[20:21], v[108:109]
	ds_read_b128 v[78:81], v100 offset:18016
	ds_read_b128 v[74:77], v100 offset:18032
	v_add_f32_e32 v130, v106, v107
	v_add_f32_e32 v131, v108, v109
	v_pk_mul_f32 v[114:115], v[84:85], v[2:3]
	v_add_f32_dpp v130, v130, v130 quad_perm:[1,0,3,2] row_mask:0xf bank_mask:0xf bound_ctrl:1
	v_add_f32_dpp v131, v131, v131 quad_perm:[1,0,3,2] row_mask:0xf bank_mask:0xf bound_ctrl:1
	v_pk_mul_f32 v[116:117], v[86:87], v[4:5]
	v_add_f32_dpp v130, v130, v130 quad_perm:[2,3,0,1] row_mask:0xf bank_mask:0xf bound_ctrl:1
	v_add_f32_dpp v131, v131, v131 quad_perm:[2,3,0,1] row_mask:0xf bank_mask:0xf bound_ctrl:1
	v_pk_mul_f32 v[118:119], v[88:89], v[6:7]
	v_add_f32_dpp v130, v130, v130 row_half_mirror row_mask:0xf bank_mask:0xf bound_ctrl:1
	v_add_f32_dpp v131, v131, v131 row_half_mirror row_mask:0xf bank_mask:0xf bound_ctrl:1
	v_pk_mul_f32 v[120:121], v[90:91], v[8:9]
	ds_read_b128 v[62:65], v100 offset:18272
	ds_read_b128 v[58:61], v100 offset:18288
	v_mul_f32_e32 v132, v130, v96
	v_mul_f32_e32 v133, v97, v94
	ds_read_b32 v0, v101 offset:18528
	v_add_f32_e32 v131, v132, v131
	ds_read_b64 v[98:99], v1 offset:18784
	v_add_f32_e32 v131, v133, v131
	v_pk_fma_f32 v[114:115], v[130:131], v[26:27], v[114:115] op_sel_hi:[0,1,1]
	v_pk_fma_f32 v[116:117], v[130:131], v[28:29], v[116:117] op_sel_hi:[0,1,1]
	v_cvt_pk_bf16_f32 v132, v131, v131
	v_pk_fma_f32 v[84:85], v[94:95], v[10:11], v[114:115] op_sel_hi:[0,1,1]
	global_store_short v154, v132, s[100:101]
	v_pk_fma_f32 v[118:119], v[130:131], v[30:31], v[118:119] op_sel_hi:[0,1,1]
	v_pk_fma_f32 v[86:87], v[94:95], v[12:13], v[116:117] op_sel_hi:[0,1,1]
	v_pk_fma_f32 v[120:121], v[130:131], v[32:33], v[120:121] op_sel_hi:[0,1,1]
	v_pk_fma_f32 v[88:89], v[94:95], v[14:15], v[118:119] op_sel_hi:[0,1,1]
	v_pk_fma_f32 v[90:91], v[94:95], v[16:17], v[120:121] op_sel_hi:[0,1,1]
	s_waitcnt lgkmcnt(0)
	v_pk_fma_f32 v[110:111], v[84:85], v[78:79], 0 op_sel_hi:[1,1,0]
	v_pk_fma_f32 v[112:113], v[84:85], v[70:71], 0 op_sel_hi:[1,1,0]
	ds_read_b128 v[22:25], v100 offset:18816
	ds_read_b128 v[18:21], v100 offset:18832
	v_pk_fma_f32 v[110:111], v[86:87], v[80:81], v[110:111]
	v_pk_fma_f32 v[112:113], v[86:87], v[72:73], v[112:113]
	ds_read_b128 v[2:5], v100 offset:19072
	ds_read_b128 v[6:9], v100 offset:19088
	v_pk_fma_f32 v[110:111], v[88:89], v[74:75], v[110:111]
	v_pk_fma_f32 v[112:113], v[88:89], v[66:67], v[112:113]
	ds_read_b128 v[10:13], v100 offset:19328
	ds_read_b128 v[14:17], v100 offset:19344
	v_pk_fma_f32 v[110:111], v[90:91], v[76:77], v[110:111]
	v_pk_fma_f32 v[112:113], v[90:91], v[68:69], v[112:113]
	ds_read_b128 v[34:37], v100 offset:19584
	ds_read_b128 v[38:41], v100 offset:19600
	v_add_f32_e32 v140, v110, v111
	v_add_f32_e32 v141, v112, v113
	v_pk_mul_f32 v[114:115], v[84:85], v[50:51]
	v_add_f32_dpp v140, v140, v140 quad_perm:[1,0,3,2] row_mask:0xf bank_mask:0xf bound_ctrl:1
	v_add_f32_dpp v141, v141, v141 quad_perm:[1,0,3,2] row_mask:0xf bank_mask:0xf bound_ctrl:1
	v_pk_mul_f32 v[116:117], v[86:87], v[52:53]
	v_add_f32_dpp v140, v140, v140 quad_perm:[2,3,0,1] row_mask:0xf bank_mask:0xf bound_ctrl:1
	v_add_f32_dpp v141, v141, v141 quad_perm:[2,3,0,1] row_mask:0xf bank_mask:0xf bound_ctrl:1
	v_pk_mul_f32 v[118:119], v[88:89], v[46:47]
	v_add_f32_dpp v140, v140, v140 row_half_mirror row_mask:0xf bank_mask:0xf bound_ctrl:1
	v_add_f32_dpp v141, v141, v141 row_half_mirror row_mask:0xf bank_mask:0xf bound_ctrl:1
	v_pk_mul_f32 v[120:121], v[90:91], v[48:49]
	ds_read_b128 v[26:29], v100 offset:19840
	ds_read_b128 v[30:33], v100 offset:19856
	v_mul_f32_e32 v142, v140, v98
	v_mul_f32_e32 v143, v99, v0
	ds_read_b32 v94, v101 offset:20096
	v_add_f32_e32 v141, v142, v141
	ds_read_b64 v[96:97], v1 offset:20352
	v_add_f32_e32 v141, v143, v141
	v_pk_fma_f32 v[114:115], v[140:141], v[62:63], v[114:115] op_sel_hi:[0,1,1]
	v_pk_fma_f32 v[116:117], v[140:141], v[64:65], v[116:117] op_sel_hi:[0,1,1]
	v_cvt_pk_bf16_f32 v142, v141, v141
	v_pk_fma_f32 v[84:85], v[0:1], v[54:55], v[114:115] op_sel_hi:[0,1,1]
	global_store_short v155, v142, s[100:101]
	v_pk_fma_f32 v[118:119], v[140:141], v[58:59], v[118:119] op_sel_hi:[0,1,1]
	v_pk_fma_f32 v[86:87], v[0:1], v[56:57], v[116:117] op_sel_hi:[0,1,1]
	v_pk_fma_f32 v[120:121], v[140:141], v[60:61], v[120:121] op_sel_hi:[0,1,1]
	v_pk_fma_f32 v[88:89], v[0:1], v[42:43], v[118:119] op_sel_hi:[0,1,1]
	v_pk_fma_f32 v[90:91], v[0:1], v[44:45], v[120:121] op_sel_hi:[0,1,1]
	s_waitcnt lgkmcnt(0)
	v_pk_fma_f32 v[106:107], v[84:85], v[34:35], 0 op_sel_hi:[1,1,0]
	v_pk_fma_f32 v[108:109], v[84:85], v[22:23], 0 op_sel_hi:[1,1,0]
	ds_read_b128 v[70:73], v100 offset:20384
	ds_read_b128 v[66:69], v100 offset:20400
	v_pk_fma_f32 v[106:107], v[86:87], v[36:37], v[106:107]
	v_pk_fma_f32 v[108:109], v[86:87], v[24:25], v[108:109]
	ds_read_b128 v[50:53], v100 offset:20640
	ds_read_b128 v[46:49], v100 offset:20656
	v_pk_fma_f32 v[106:107], v[88:89], v[38:39], v[106:107]
	v_pk_fma_f32 v[108:109], v[88:89], v[18:19], v[108:109]
	ds_read_b128 v[54:57], v100 offset:20896
	ds_read_b128 v[42:45], v100 offset:20912
	v_pk_fma_f32 v[106:107], v[90:91], v[40:41], v[106:107]
	v_pk_fma_f32 v[108:109], v[90:91], v[20:21], v[108:109]
	ds_read_b128 v[78:81], v100 offset:21152
	ds_read_b128 v[74:77], v100 offset:21168
	v_add_f32_e32 v130, v106, v107
	v_add_f32_e32 v131, v108, v109
	v_pk_mul_f32 v[114:115], v[84:85], v[2:3]
	v_add_f32_dpp v130, v130, v130 quad_perm:[1,0,3,2] row_mask:0xf bank_mask:0xf bound_ctrl:1
	v_add_f32_dpp v131, v131, v131 quad_perm:[1,0,3,2] row_mask:0xf bank_mask:0xf bound_ctrl:1
	v_pk_mul_f32 v[116:117], v[86:87], v[4:5]
	v_add_f32_dpp v130, v130, v130 quad_perm:[2,3,0,1] row_mask:0xf bank_mask:0xf bound_ctrl:1
	v_add_f32_dpp v131, v131, v131 quad_perm:[2,3,0,1] row_mask:0xf bank_mask:0xf bound_ctrl:1
	v_pk_mul_f32 v[118:119], v[88:89], v[6:7]
	v_add_f32_dpp v130, v130, v130 row_half_mirror row_mask:0xf bank_mask:0xf bound_ctrl:1
	v_add_f32_dpp v131, v131, v131 row_half_mirror row_mask:0xf bank_mask:0xf bound_ctrl:1
	v_pk_mul_f32 v[120:121], v[90:91], v[8:9]
	ds_read_b128 v[62:65], v100 offset:21408
	ds_read_b128 v[58:61], v100 offset:21424
	v_mul_f32_e32 v132, v130, v96
	v_mul_f32_e32 v133, v97, v94
	ds_read_b32 v0, v101 offset:21664
	v_add_f32_e32 v131, v132, v131
	ds_read_b64 v[98:99], v1 offset:21920
	v_add_f32_e32 v131, v133, v131
	v_pk_fma_f32 v[114:115], v[130:131], v[26:27], v[114:115] op_sel_hi:[0,1,1]
	v_pk_fma_f32 v[116:117], v[130:131], v[28:29], v[116:117] op_sel_hi:[0,1,1]
	v_cvt_pk_bf16_f32 v132, v131, v131
	v_pk_fma_f32 v[84:85], v[94:95], v[10:11], v[114:115] op_sel_hi:[0,1,1]
	global_store_short v156, v132, s[100:101]
	v_pk_fma_f32 v[118:119], v[130:131], v[30:31], v[118:119] op_sel_hi:[0,1,1]
	v_pk_fma_f32 v[86:87], v[94:95], v[12:13], v[116:117] op_sel_hi:[0,1,1]
	v_pk_fma_f32 v[120:121], v[130:131], v[32:33], v[120:121] op_sel_hi:[0,1,1]
	v_pk_fma_f32 v[88:89], v[94:95], v[14:15], v[118:119] op_sel_hi:[0,1,1]
	v_pk_fma_f32 v[90:91], v[94:95], v[16:17], v[120:121] op_sel_hi:[0,1,1]
	s_waitcnt lgkmcnt(0)
	v_pk_fma_f32 v[110:111], v[84:85], v[78:79], 0 op_sel_hi:[1,1,0]
	v_pk_fma_f32 v[112:113], v[84:85], v[70:71], 0 op_sel_hi:[1,1,0]
	ds_read_b128 v[22:25], v100 offset:21952
	ds_read_b128 v[18:21], v100 offset:21968
	v_pk_fma_f32 v[110:111], v[86:87], v[80:81], v[110:111]
	v_pk_fma_f32 v[112:113], v[86:87], v[72:73], v[112:113]
	ds_read_b128 v[2:5], v100 offset:22208
	ds_read_b128 v[6:9], v100 offset:22224
	v_pk_fma_f32 v[110:111], v[88:89], v[74:75], v[110:111]
	v_pk_fma_f32 v[112:113], v[88:89], v[66:67], v[112:113]
	ds_read_b128 v[10:13], v100 offset:22464
	ds_read_b128 v[14:17], v100 offset:22480
	v_pk_fma_f32 v[110:111], v[90:91], v[76:77], v[110:111]
	v_pk_fma_f32 v[112:113], v[90:91], v[68:69], v[112:113]
	ds_read_b128 v[34:37], v100 offset:22720
	ds_read_b128 v[38:41], v100 offset:22736
	v_add_f32_e32 v140, v110, v111
	v_add_f32_e32 v141, v112, v113
	v_pk_mul_f32 v[114:115], v[84:85], v[50:51]
	v_add_f32_dpp v140, v140, v140 quad_perm:[1,0,3,2] row_mask:0xf bank_mask:0xf bound_ctrl:1
	v_add_f32_dpp v141, v141, v141 quad_perm:[1,0,3,2] row_mask:0xf bank_mask:0xf bound_ctrl:1
	v_pk_mul_f32 v[116:117], v[86:87], v[52:53]
	v_add_f32_dpp v140, v140, v140 quad_perm:[2,3,0,1] row_mask:0xf bank_mask:0xf bound_ctrl:1
	v_add_f32_dpp v141, v141, v141 quad_perm:[2,3,0,1] row_mask:0xf bank_mask:0xf bound_ctrl:1
	v_pk_mul_f32 v[118:119], v[88:89], v[46:47]
	v_add_f32_dpp v140, v140, v140 row_half_mirror row_mask:0xf bank_mask:0xf bound_ctrl:1
	v_add_f32_dpp v141, v141, v141 row_half_mirror row_mask:0xf bank_mask:0xf bound_ctrl:1
	v_pk_mul_f32 v[120:121], v[90:91], v[48:49]
	ds_read_b128 v[26:29], v100 offset:22976
	ds_read_b128 v[30:33], v100 offset:22992
	v_mul_f32_e32 v142, v140, v98
	v_mul_f32_e32 v143, v99, v0
	ds_read_b32 v94, v101 offset:23232
	v_add_f32_e32 v141, v142, v141
	ds_read_b64 v[96:97], v1 offset:23488
	v_add_f32_e32 v141, v143, v141
	v_pk_fma_f32 v[114:115], v[140:141], v[62:63], v[114:115] op_sel_hi:[0,1,1]
	v_pk_fma_f32 v[116:117], v[140:141], v[64:65], v[116:117] op_sel_hi:[0,1,1]
	v_cvt_pk_bf16_f32 v142, v141, v141
	v_pk_fma_f32 v[84:85], v[0:1], v[54:55], v[114:115] op_sel_hi:[0,1,1]
	global_store_short v157, v142, s[100:101]
	v_pk_fma_f32 v[118:119], v[140:141], v[58:59], v[118:119] op_sel_hi:[0,1,1]
	v_pk_fma_f32 v[86:87], v[0:1], v[56:57], v[116:117] op_sel_hi:[0,1,1]
	v_pk_fma_f32 v[120:121], v[140:141], v[60:61], v[120:121] op_sel_hi:[0,1,1]
	v_pk_fma_f32 v[88:89], v[0:1], v[42:43], v[118:119] op_sel_hi:[0,1,1]
	v_pk_fma_f32 v[90:91], v[0:1], v[44:45], v[120:121] op_sel_hi:[0,1,1]
	s_waitcnt lgkmcnt(0)
	v_pk_fma_f32 v[106:107], v[84:85], v[34:35], 0 op_sel_hi:[1,1,0]
	v_pk_fma_f32 v[108:109], v[84:85], v[22:23], 0 op_sel_hi:[1,1,0]
	ds_read_b128 v[70:73], v100 offset:23520
	ds_read_b128 v[66:69], v100 offset:23536
	v_pk_fma_f32 v[106:107], v[86:87], v[36:37], v[106:107]
	v_pk_fma_f32 v[108:109], v[86:87], v[24:25], v[108:109]
	ds_read_b128 v[50:53], v100 offset:23776
	ds_read_b128 v[46:49], v100 offset:23792
	v_pk_fma_f32 v[106:107], v[88:89], v[38:39], v[106:107]
	v_pk_fma_f32 v[108:109], v[88:89], v[18:19], v[108:109]
	ds_read_b128 v[54:57], v100 offset:24032
	ds_read_b128 v[42:45], v100 offset:24048
	v_pk_fma_f32 v[106:107], v[90:91], v[40:41], v[106:107]
	v_pk_fma_f32 v[108:109], v[90:91], v[20:21], v[108:109]
	ds_read_b128 v[78:81], v100 offset:24288
	ds_read_b128 v[74:77], v100 offset:24304
	v_add_f32_e32 v130, v106, v107
	v_add_f32_e32 v131, v108, v109
	v_pk_mul_f32 v[114:115], v[84:85], v[2:3]
	v_add_f32_dpp v130, v130, v130 quad_perm:[1,0,3,2] row_mask:0xf bank_mask:0xf bound_ctrl:1
	v_add_f32_dpp v131, v131, v131 quad_perm:[1,0,3,2] row_mask:0xf bank_mask:0xf bound_ctrl:1
	v_pk_mul_f32 v[116:117], v[86:87], v[4:5]
	v_add_f32_dpp v130, v130, v130 quad_perm:[2,3,0,1] row_mask:0xf bank_mask:0xf bound_ctrl:1
	v_add_f32_dpp v131, v131, v131 quad_perm:[2,3,0,1] row_mask:0xf bank_mask:0xf bound_ctrl:1
	v_pk_mul_f32 v[118:119], v[88:89], v[6:7]
	v_add_f32_dpp v130, v130, v130 row_half_mirror row_mask:0xf bank_mask:0xf bound_ctrl:1
	v_add_f32_dpp v131, v131, v131 row_half_mirror row_mask:0xf bank_mask:0xf bound_ctrl:1
	v_pk_mul_f32 v[120:121], v[90:91], v[8:9]
	ds_read_b128 v[62:65], v100 offset:24544
	ds_read_b128 v[58:61], v100 offset:24560
	v_mul_f32_e32 v132, v130, v96
	v_mul_f32_e32 v133, v97, v94
	ds_read_b32 v0, v101 offset:24800
	v_add_f32_e32 v131, v132, v131
	ds_read_b64 v[98:99], v1 offset:25056
	v_add_f32_e32 v131, v133, v131
	v_pk_fma_f32 v[114:115], v[130:131], v[26:27], v[114:115] op_sel_hi:[0,1,1]
	v_pk_fma_f32 v[116:117], v[130:131], v[28:29], v[116:117] op_sel_hi:[0,1,1]
	v_cvt_pk_bf16_f32 v132, v131, v131
	v_pk_fma_f32 v[84:85], v[94:95], v[10:11], v[114:115] op_sel_hi:[0,1,1]
	global_store_short v158, v132, s[100:101]
	v_pk_fma_f32 v[118:119], v[130:131], v[30:31], v[118:119] op_sel_hi:[0,1,1]
	v_pk_fma_f32 v[86:87], v[94:95], v[12:13], v[116:117] op_sel_hi:[0,1,1]
	v_pk_fma_f32 v[120:121], v[130:131], v[32:33], v[120:121] op_sel_hi:[0,1,1]
	v_pk_fma_f32 v[88:89], v[94:95], v[14:15], v[118:119] op_sel_hi:[0,1,1]
	v_pk_fma_f32 v[90:91], v[94:95], v[16:17], v[120:121] op_sel_hi:[0,1,1]
	s_waitcnt lgkmcnt(0)
	v_pk_fma_f32 v[110:111], v[84:85], v[78:79], 0 op_sel_hi:[1,1,0]
	v_pk_fma_f32 v[112:113], v[84:85], v[70:71], 0 op_sel_hi:[1,1,0]
	v_pk_fma_f32 v[110:111], v[86:87], v[80:81], v[110:111]
	v_pk_fma_f32 v[112:113], v[86:87], v[72:73], v[112:113]
	v_pk_fma_f32 v[110:111], v[88:89], v[74:75], v[110:111]
	v_pk_fma_f32 v[112:113], v[88:89], v[66:67], v[112:113]
	v_pk_fma_f32 v[110:111], v[90:91], v[76:77], v[110:111]
	v_pk_fma_f32 v[112:113], v[90:91], v[68:69], v[112:113]
	v_add_f32_e32 v140, v110, v111
	v_add_f32_e32 v141, v112, v113
	v_pk_mul_f32 v[114:115], v[84:85], v[50:51]
	v_add_f32_dpp v140, v140, v140 quad_perm:[1,0,3,2] row_mask:0xf bank_mask:0xf bound_ctrl:1
	v_add_f32_dpp v141, v141, v141 quad_perm:[1,0,3,2] row_mask:0xf bank_mask:0xf bound_ctrl:1
	v_pk_mul_f32 v[116:117], v[86:87], v[52:53]
	v_add_f32_dpp v140, v140, v140 quad_perm:[2,3,0,1] row_mask:0xf bank_mask:0xf bound_ctrl:1
	v_add_f32_dpp v141, v141, v141 quad_perm:[2,3,0,1] row_mask:0xf bank_mask:0xf bound_ctrl:1
	v_pk_mul_f32 v[118:119], v[88:89], v[46:47]
	v_add_f32_dpp v140, v140, v140 row_half_mirror row_mask:0xf bank_mask:0xf bound_ctrl:1
	v_add_f32_dpp v141, v141, v141 row_half_mirror row_mask:0xf bank_mask:0xf bound_ctrl:1
	v_pk_mul_f32 v[120:121], v[90:91], v[48:49]
	v_mul_f32_e32 v142, v140, v98
	v_mul_f32_e32 v143, v99, v0
	v_add_f32_e32 v141, v142, v141
	v_add_f32_e32 v141, v143, v141
	v_pk_fma_f32 v[114:115], v[140:141], v[62:63], v[114:115] op_sel_hi:[0,1,1]
	v_pk_fma_f32 v[116:117], v[140:141], v[64:65], v[116:117] op_sel_hi:[0,1,1]
	v_cvt_pk_bf16_f32 v142, v141, v141
	v_pk_fma_f32 v[84:85], v[0:1], v[54:55], v[114:115] op_sel_hi:[0,1,1]
	global_store_short v159, v142, s[100:101]
	v_pk_fma_f32 v[118:119], v[140:141], v[58:59], v[118:119] op_sel_hi:[0,1,1]
	v_pk_fma_f32 v[86:87], v[0:1], v[56:57], v[116:117] op_sel_hi:[0,1,1]
	v_pk_fma_f32 v[120:121], v[140:141], v[60:61], v[120:121] op_sel_hi:[0,1,1]
	v_pk_fma_f32 v[88:89], v[0:1], v[42:43], v[118:119] op_sel_hi:[0,1,1]
	v_pk_fma_f32 v[90:91], v[0:1], v[44:45], v[120:121] op_sel_hi:[0,1,1]

.LBB0_869:
	v_readfirstlane_b32 s100, v92
	v_readfirstlane_b32 s101, v93
	s_sub_u32 s100, s100, m0
	s_subb_u32 s101, s101, 0
	s_waitcnt lgkmcnt(0)
	v_pk_fma_f32 v[106:107], v[84:85], v[34:35], 0 op_sel_hi:[1,1,0]
	v_pk_fma_f32 v[108:109], v[84:85], v[22:23], 0 op_sel_hi:[1,1,0]
	ds_read_b128 v[70:73], v100 offset:26656
	ds_read_b128 v[66:69], v100 offset:26672
	v_pk_fma_f32 v[106:107], v[86:87], v[36:37], v[106:107]
	v_pk_fma_f32 v[108:109], v[86:87], v[24:25], v[108:109]
	ds_read_b128 v[50:53], v100 offset:26912
	ds_read_b128 v[46:49], v100 offset:26928
	v_pk_fma_f32 v[106:107], v[88:89], v[38:39], v[106:107]
	v_pk_fma_f32 v[108:109], v[88:89], v[18:19], v[108:109]
	ds_read_b128 v[54:57], v100 offset:27168
	ds_read_b128 v[42:45], v100 offset:27184
	v_pk_fma_f32 v[106:107], v[90:91], v[40:41], v[106:107]
	v_pk_fma_f32 v[108:109], v[90:91], v[20:21], v[108:109]
	ds_read_b128 v[78:81], v100 offset:27424
	ds_read_b128 v[74:77], v100 offset:27440
	v_add_f32_e32 v130, v106, v107
	v_add_f32_e32 v131, v108, v109
	v_pk_mul_f32 v[114:115], v[84:85], v[2:3]
	v_add_f32_dpp v130, v130, v130 quad_perm:[1,0,3,2] row_mask:0xf bank_mask:0xf bound_ctrl:1
	v_add_f32_dpp v131, v131, v131 quad_perm:[1,0,3,2] row_mask:0xf bank_mask:0xf bound_ctrl:1
	v_pk_mul_f32 v[116:117], v[86:87], v[4:5]
	v_add_f32_dpp v130, v130, v130 quad_perm:[2,3,0,1] row_mask:0xf bank_mask:0xf bound_ctrl:1
	v_add_f32_dpp v131, v131, v131 quad_perm:[2,3,0,1] row_mask:0xf bank_mask:0xf bound_ctrl:1
	v_pk_mul_f32 v[118:119], v[88:89], v[6:7]
	v_add_f32_dpp v130, v130, v130 row_half_mirror row_mask:0xf bank_mask:0xf bound_ctrl:1
	v_add_f32_dpp v131, v131, v131 row_half_mirror row_mask:0xf bank_mask:0xf bound_ctrl:1
	v_pk_mul_f32 v[120:121], v[90:91], v[8:9]
	ds_read_b128 v[62:65], v100 offset:27680
	ds_read_b128 v[58:61], v100 offset:27696
	v_mul_f32_e32 v132, v130, v96
	v_mul_f32_e32 v133, v97, v94
	ds_read_b32 v0, v101 offset:27936
	v_add_f32_e32 v131, v132, v131
	ds_read_b64 v[98:99], v1 offset:28192
	v_add_f32_e32 v131, v133, v131
	v_pk_fma_f32 v[114:115], v[130:131], v[26:27], v[114:115] op_sel_hi:[0,1,1]
	v_pk_fma_f32 v[116:117], v[130:131], v[28:29], v[116:117] op_sel_hi:[0,1,1]
	v_cvt_pk_bf16_f32 v132, v131, v131
	v_pk_fma_f32 v[84:85], v[94:95], v[10:11], v[114:115] op_sel_hi:[0,1,1]
	global_store_short v144, v132, s[100:101]
	v_pk_fma_f32 v[118:119], v[130:131], v[30:31], v[118:119] op_sel_hi:[0,1,1]
	v_pk_fma_f32 v[86:87], v[94:95], v[12:13], v[116:117] op_sel_hi:[0,1,1]
	v_pk_fma_f32 v[120:121], v[130:131], v[32:33], v[120:121] op_sel_hi:[0,1,1]
	v_pk_fma_f32 v[88:89], v[94:95], v[14:15], v[118:119] op_sel_hi:[0,1,1]
	v_pk_fma_f32 v[90:91], v[94:95], v[16:17], v[120:121] op_sel_hi:[0,1,1]
	s_waitcnt lgkmcnt(0)
	v_pk_fma_f32 v[110:111], v[84:85], v[78:79], 0 op_sel_hi:[1,1,0]
	v_pk_fma_f32 v[112:113], v[84:85], v[70:71], 0 op_sel_hi:[1,1,0]
	ds_read_b128 v[22:25], v100 offset:28224
	ds_read_b128 v[18:21], v100 offset:28240
	v_pk_fma_f32 v[110:111], v[86:87], v[80:81], v[110:111]
	v_pk_fma_f32 v[112:113], v[86:87], v[72:73], v[112:113]
	ds_read_b128 v[2:5], v100 offset:28480
	ds_read_b128 v[6:9], v100 offset:28496
	v_pk_fma_f32 v[110:111], v[88:89], v[74:75], v[110:111]
	v_pk_fma_f32 v[112:113], v[88:89], v[66:67], v[112:113]
	ds_read_b128 v[10:13], v100 offset:28736
	ds_read_b128 v[14:17], v100 offset:28752
	v_pk_fma_f32 v[110:111], v[90:91], v[76:77], v[110:111]
	v_pk_fma_f32 v[112:113], v[90:91], v[68:69], v[112:113]
	ds_read_b128 v[34:37], v100 offset:28992
	ds_read_b128 v[38:41], v100 offset:29008
	v_add_f32_e32 v140, v110, v111
	v_add_f32_e32 v141, v112, v113
	v_pk_mul_f32 v[114:115], v[84:85], v[50:51]
	v_add_f32_dpp v140, v140, v140 quad_perm:[1,0,3,2] row_mask:0xf bank_mask:0xf bound_ctrl:1
	v_add_f32_dpp v141, v141, v141 quad_perm:[1,0,3,2] row_mask:0xf bank_mask:0xf bound_ctrl:1
	v_pk_mul_f32 v[116:117], v[86:87], v[52:53]
	v_add_f32_dpp v140, v140, v140 quad_perm:[2,3,0,1] row_mask:0xf bank_mask:0xf bound_ctrl:1
	v_add_f32_dpp v141, v141, v141 quad_perm:[2,3,0,1] row_mask:0xf bank_mask:0xf bound_ctrl:1
	v_pk_mul_f32 v[118:119], v[88:89], v[46:47]
	v_add_f32_dpp v140, v140, v140 row_half_mirror row_mask:0xf bank_mask:0xf bound_ctrl:1
	v_add_f32_dpp v141, v141, v141 row_half_mirror row_mask:0xf bank_mask:0xf bound_ctrl:1
	v_pk_mul_f32 v[120:121], v[90:91], v[48:49]
	ds_read_b128 v[26:29], v100 offset:29248
	ds_read_b128 v[30:33], v100 offset:29264
	v_mul_f32_e32 v142, v140, v98
	v_mul_f32_e32 v143, v99, v0
	ds_read_b32 v94, v101 offset:29504
	v_add_f32_e32 v141, v142, v141
	ds_read_b64 v[96:97], v1 offset:29760
	v_add_f32_e32 v141, v143, v141
	v_pk_fma_f32 v[114:115], v[140:141], v[62:63], v[114:115] op_sel_hi:[0,1,1]
	v_pk_fma_f32 v[116:117], v[140:141], v[64:65], v[116:117] op_sel_hi:[0,1,1]
	v_cvt_pk_bf16_f32 v142, v141, v141
	v_pk_fma_f32 v[84:85], v[0:1], v[54:55], v[114:115] op_sel_hi:[0,1,1]
	global_store_short v145, v142, s[100:101]
	v_pk_fma_f32 v[118:119], v[140:141], v[58:59], v[118:119] op_sel_hi:[0,1,1]
	v_pk_fma_f32 v[86:87], v[0:1], v[56:57], v[116:117] op_sel_hi:[0,1,1]
	v_pk_fma_f32 v[120:121], v[140:141], v[60:61], v[120:121] op_sel_hi:[0,1,1]
	v_pk_fma_f32 v[88:89], v[0:1], v[42:43], v[118:119] op_sel_hi:[0,1,1]
	v_pk_fma_f32 v[90:91], v[0:1], v[44:45], v[120:121] op_sel_hi:[0,1,1]
	s_waitcnt lgkmcnt(0)
	v_pk_fma_f32 v[106:107], v[84:85], v[34:35], 0 op_sel_hi:[1,1,0]
	v_pk_fma_f32 v[108:109], v[84:85], v[22:23], 0 op_sel_hi:[1,1,0]
	ds_read_b128 v[70:73], v100 offset:29792
	ds_read_b128 v[66:69], v100 offset:29808
	v_pk_fma_f32 v[106:107], v[86:87], v[36:37], v[106:107]
	v_pk_fma_f32 v[108:109], v[86:87], v[24:25], v[108:109]
	ds_read_b128 v[50:53], v100 offset:30048
	ds_read_b128 v[46:49], v100 offset:30064
	v_pk_fma_f32 v[106:107], v[88:89], v[38:39], v[106:107]
	v_pk_fma_f32 v[108:109], v[88:89], v[18:19], v[108:109]
	ds_read_b128 v[54:57], v100 offset:30304
	ds_read_b128 v[42:45], v100 offset:30320
	v_pk_fma_f32 v[106:107], v[90:91], v[40:41], v[106:107]
	v_pk_fma_f32 v[108:109], v[90:91], v[20:21], v[108:109]
	ds_read_b128 v[78:81], v100 offset:30560
	ds_read_b128 v[74:77], v100 offset:30576
	v_add_f32_e32 v130, v106, v107
	v_add_f32_e32 v131, v108, v109
	v_pk_mul_f32 v[114:115], v[84:85], v[2:3]
	v_add_f32_dpp v130, v130, v130 quad_perm:[1,0,3,2] row_mask:0xf bank_mask:0xf bound_ctrl:1
	v_add_f32_dpp v131, v131, v131 quad_perm:[1,0,3,2] row_mask:0xf bank_mask:0xf bound_ctrl:1
	v_pk_mul_f32 v[116:117], v[86:87], v[4:5]
	v_add_f32_dpp v130, v130, v130 quad_perm:[2,3,0,1] row_mask:0xf bank_mask:0xf bound_ctrl:1
	v_add_f32_dpp v131, v131, v131 quad_perm:[2,3,0,1] row_mask:0xf bank_mask:0xf bound_ctrl:1
	v_pk_mul_f32 v[118:119], v[88:89], v[6:7]
	v_add_f32_dpp v130, v130, v130 row_half_mirror row_mask:0xf bank_mask:0xf bound_ctrl:1
	v_add_f32_dpp v131, v131, v131 row_half_mirror row_mask:0xf bank_mask:0xf bound_ctrl:1
	v_pk_mul_f32 v[120:121], v[90:91], v[8:9]
	ds_read_b128 v[62:65], v100 offset:30816
	ds_read_b128 v[58:61], v100 offset:30832
	v_mul_f32_e32 v132, v130, v96
	v_mul_f32_e32 v133, v97, v94
	ds_read_b32 v0, v101 offset:31072
	v_add_f32_e32 v131, v132, v131
	ds_read_b64 v[98:99], v1 offset:31328
	v_add_f32_e32 v131, v133, v131
	v_pk_fma_f32 v[114:115], v[130:131], v[26:27], v[114:115] op_sel_hi:[0,1,1]
	v_pk_fma_f32 v[116:117], v[130:131], v[28:29], v[116:117] op_sel_hi:[0,1,1]
	v_cvt_pk_bf16_f32 v132, v131, v131
	v_pk_fma_f32 v[84:85], v[94:95], v[10:11], v[114:115] op_sel_hi:[0,1,1]
	global_store_short v146, v132, s[100:101]
	v_pk_fma_f32 v[118:119], v[130:131], v[30:31], v[118:119] op_sel_hi:[0,1,1]
	v_pk_fma_f32 v[86:87], v[94:95], v[12:13], v[116:117] op_sel_hi:[0,1,1]
	v_pk_fma_f32 v[120:121], v[130:131], v[32:33], v[120:121] op_sel_hi:[0,1,1]
	v_pk_fma_f32 v[88:89], v[94:95], v[14:15], v[118:119] op_sel_hi:[0,1,1]
	v_pk_fma_f32 v[90:91], v[94:95], v[16:17], v[120:121] op_sel_hi:[0,1,1]
	s_waitcnt lgkmcnt(0)
	v_pk_fma_f32 v[110:111], v[84:85], v[78:79], 0 op_sel_hi:[1,1,0]
	v_pk_fma_f32 v[112:113], v[84:85], v[70:71], 0 op_sel_hi:[1,1,0]
	ds_read_b128 v[22:25], v100 offset:31360
	ds_read_b128 v[18:21], v100 offset:31376
	v_pk_fma_f32 v[110:111], v[86:87], v[80:81], v[110:111]
	v_pk_fma_f32 v[112:113], v[86:87], v[72:73], v[112:113]
	ds_read_b128 v[2:5], v100 offset:31616
	ds_read_b128 v[6:9], v100 offset:31632
	v_pk_fma_f32 v[110:111], v[88:89], v[74:75], v[110:111]
	v_pk_fma_f32 v[112:113], v[88:89], v[66:67], v[112:113]
	ds_read_b128 v[10:13], v100 offset:31872
	ds_read_b128 v[14:17], v100 offset:31888
	v_pk_fma_f32 v[110:111], v[90:91], v[76:77], v[110:111]
	v_pk_fma_f32 v[112:113], v[90:91], v[68:69], v[112:113]
	ds_read_b128 v[34:37], v100 offset:32128
	ds_read_b128 v[38:41], v100 offset:32144
	v_add_f32_e32 v140, v110, v111
	v_add_f32_e32 v141, v112, v113
	v_pk_mul_f32 v[114:115], v[84:85], v[50:51]
	v_add_f32_dpp v140, v140, v140 quad_perm:[1,0,3,2] row_mask:0xf bank_mask:0xf bound_ctrl:1
	v_add_f32_dpp v141, v141, v141 quad_perm:[1,0,3,2] row_mask:0xf bank_mask:0xf bound_ctrl:1
	v_pk_mul_f32 v[116:117], v[86:87], v[52:53]
	v_add_f32_dpp v140, v140, v140 quad_perm:[2,3,0,1] row_mask:0xf bank_mask:0xf bound_ctrl:1
	v_add_f32_dpp v141, v141, v141 quad_perm:[2,3,0,1] row_mask:0xf bank_mask:0xf bound_ctrl:1
	v_pk_mul_f32 v[118:119], v[88:89], v[46:47]
	v_add_f32_dpp v140, v140, v140 row_half_mirror row_mask:0xf bank_mask:0xf bound_ctrl:1
	v_add_f32_dpp v141, v141, v141 row_half_mirror row_mask:0xf bank_mask:0xf bound_ctrl:1
	v_pk_mul_f32 v[120:121], v[90:91], v[48:49]
	ds_read_b128 v[26:29], v100 offset:32384
	ds_read_b128 v[30:33], v100 offset:32400
	v_mul_f32_e32 v142, v140, v98
	v_mul_f32_e32 v143, v99, v0
	ds_read_b32 v94, v101 offset:32640
	v_add_f32_e32 v141, v142, v141
	ds_read_b64 v[96:97], v1 offset:32896
	v_add_f32_e32 v141, v143, v141
	v_pk_fma_f32 v[114:115], v[140:141], v[62:63], v[114:115] op_sel_hi:[0,1,1]
	v_pk_fma_f32 v[116:117], v[140:141], v[64:65], v[116:117] op_sel_hi:[0,1,1]
	v_cvt_pk_bf16_f32 v142, v141, v141
	v_pk_fma_f32 v[84:85], v[0:1], v[54:55], v[114:115] op_sel_hi:[0,1,1]
	global_store_short v147, v142, s[100:101]
	v_pk_fma_f32 v[118:119], v[140:141], v[58:59], v[118:119] op_sel_hi:[0,1,1]
	v_pk_fma_f32 v[86:87], v[0:1], v[56:57], v[116:117] op_sel_hi:[0,1,1]
	v_pk_fma_f32 v[120:121], v[140:141], v[60:61], v[120:121] op_sel_hi:[0,1,1]
	v_pk_fma_f32 v[88:89], v[0:1], v[42:43], v[118:119] op_sel_hi:[0,1,1]
	v_pk_fma_f32 v[90:91], v[0:1], v[44:45], v[120:121] op_sel_hi:[0,1,1]
	s_waitcnt lgkmcnt(0)
	v_pk_fma_f32 v[106:107], v[84:85], v[34:35], 0 op_sel_hi:[1,1,0]
	v_pk_fma_f32 v[108:109], v[84:85], v[22:23], 0 op_sel_hi:[1,1,0]
	ds_read_b128 v[70:73], v100 offset:32928
	ds_read_b128 v[66:69], v100 offset:32944
	v_pk_fma_f32 v[106:107], v[86:87], v[36:37], v[106:107]
	v_pk_fma_f32 v[108:109], v[86:87], v[24:25], v[108:109]
	ds_read_b128 v[50:53], v100 offset:33184
	ds_read_b128 v[46:49], v100 offset:33200
	v_pk_fma_f32 v[106:107], v[88:89], v[38:39], v[106:107]
	v_pk_fma_f32 v[108:109], v[88:89], v[18:19], v[108:109]
	ds_read_b128 v[54:57], v100 offset:33440
	ds_read_b128 v[42:45], v100 offset:33456
	v_pk_fma_f32 v[106:107], v[90:91], v[40:41], v[106:107]
	v_pk_fma_f32 v[108:109], v[90:91], v[20:21], v[108:109]
	ds_read_b128 v[78:81], v100 offset:33696
	ds_read_b128 v[74:77], v100 offset:33712
	v_add_f32_e32 v130, v106, v107
	v_add_f32_e32 v131, v108, v109
	v_pk_mul_f32 v[114:115], v[84:85], v[2:3]
	v_add_f32_dpp v130, v130, v130 quad_perm:[1,0,3,2] row_mask:0xf bank_mask:0xf bound_ctrl:1
	v_add_f32_dpp v131, v131, v131 quad_perm:[1,0,3,2] row_mask:0xf bank_mask:0xf bound_ctrl:1
	v_pk_mul_f32 v[116:117], v[86:87], v[4:5]
	v_add_f32_dpp v130, v130, v130 quad_perm:[2,3,0,1] row_mask:0xf bank_mask:0xf bound_ctrl:1
	v_add_f32_dpp v131, v131, v131 quad_perm:[2,3,0,1] row_mask:0xf bank_mask:0xf bound_ctrl:1
	v_pk_mul_f32 v[118:119], v[88:89], v[6:7]
	v_add_f32_dpp v130, v130, v130 row_half_mirror row_mask:0xf bank_mask:0xf bound_ctrl:1
	v_add_f32_dpp v131, v131, v131 row_half_mirror row_mask:0xf bank_mask:0xf bound_ctrl:1
	v_pk_mul_f32 v[120:121], v[90:91], v[8:9]
	ds_read_b128 v[62:65], v100 offset:33952
	ds_read_b128 v[58:61], v100 offset:33968
	v_mul_f32_e32 v132, v130, v96
	v_mul_f32_e32 v133, v97, v94
	ds_read_b32 v0, v101 offset:34208
	v_add_f32_e32 v131, v132, v131
	ds_read_b64 v[98:99], v1 offset:34464
	v_add_f32_e32 v131, v133, v131
	v_pk_fma_f32 v[114:115], v[130:131], v[26:27], v[114:115] op_sel_hi:[0,1,1]
	v_pk_fma_f32 v[116:117], v[130:131], v[28:29], v[116:117] op_sel_hi:[0,1,1]
	v_cvt_pk_bf16_f32 v132, v131, v131
	v_pk_fma_f32 v[84:85], v[94:95], v[10:11], v[114:115] op_sel_hi:[0,1,1]
	global_store_short v148, v132, s[100:101]
	v_pk_fma_f32 v[118:119], v[130:131], v[30:31], v[118:119] op_sel_hi:[0,1,1]
	v_pk_fma_f32 v[86:87], v[94:95], v[12:13], v[116:117] op_sel_hi:[0,1,1]
	v_pk_fma_f32 v[120:121], v[130:131], v[32:33], v[120:121] op_sel_hi:[0,1,1]
	v_pk_fma_f32 v[88:89], v[94:95], v[14:15], v[118:119] op_sel_hi:[0,1,1]
	v_pk_fma_f32 v[90:91], v[94:95], v[16:17], v[120:121] op_sel_hi:[0,1,1]
	s_waitcnt lgkmcnt(0)
	v_pk_fma_f32 v[110:111], v[84:85], v[78:79], 0 op_sel_hi:[1,1,0]
	v_pk_fma_f32 v[112:113], v[84:85], v[70:71], 0 op_sel_hi:[1,1,0]
	ds_read_b128 v[22:25], v100 offset:34496
	ds_read_b128 v[18:21], v100 offset:34512
	v_pk_fma_f32 v[110:111], v[86:87], v[80:81], v[110:111]
	v_pk_fma_f32 v[112:113], v[86:87], v[72:73], v[112:113]
	ds_read_b128 v[2:5], v100 offset:34752
	ds_read_b128 v[6:9], v100 offset:34768
	v_pk_fma_f32 v[110:111], v[88:89], v[74:75], v[110:111]
	v_pk_fma_f32 v[112:113], v[88:89], v[66:67], v[112:113]
	ds_read_b128 v[10:13], v100 offset:35008
	ds_read_b128 v[14:17], v100 offset:35024
	v_pk_fma_f32 v[110:111], v[90:91], v[76:77], v[110:111]
	v_pk_fma_f32 v[112:113], v[90:91], v[68:69], v[112:113]
	ds_read_b128 v[34:37], v100 offset:35264
	ds_read_b128 v[38:41], v100 offset:35280
	v_add_f32_e32 v140, v110, v111
	v_add_f32_e32 v141, v112, v113
	v_pk_mul_f32 v[114:115], v[84:85], v[50:51]
	v_add_f32_dpp v140, v140, v140 quad_perm:[1,0,3,2] row_mask:0xf bank_mask:0xf bound_ctrl:1
	v_add_f32_dpp v141, v141, v141 quad_perm:[1,0,3,2] row_mask:0xf bank_mask:0xf bound_ctrl:1
	v_pk_mul_f32 v[116:117], v[86:87], v[52:53]
	v_add_f32_dpp v140, v140, v140 quad_perm:[2,3,0,1] row_mask:0xf bank_mask:0xf bound_ctrl:1
	v_add_f32_dpp v141, v141, v141 quad_perm:[2,3,0,1] row_mask:0xf bank_mask:0xf bound_ctrl:1
	v_pk_mul_f32 v[118:119], v[88:89], v[46:47]
	v_add_f32_dpp v140, v140, v140 row_half_mirror row_mask:0xf bank_mask:0xf bound_ctrl:1
	v_add_f32_dpp v141, v141, v141 row_half_mirror row_mask:0xf bank_mask:0xf bound_ctrl:1
	v_pk_mul_f32 v[120:121], v[90:91], v[48:49]
	ds_read_b128 v[26:29], v100 offset:35520
	ds_read_b128 v[30:33], v100 offset:35536
	v_mul_f32_e32 v142, v140, v98
	v_mul_f32_e32 v143, v99, v0
	ds_read_b32 v94, v101 offset:35776
	v_add_f32_e32 v141, v142, v141
	ds_read_b64 v[96:97], v1 offset:36032
	v_add_f32_e32 v141, v143, v141
	v_pk_fma_f32 v[114:115], v[140:141], v[62:63], v[114:115] op_sel_hi:[0,1,1]
	v_pk_fma_f32 v[116:117], v[140:141], v[64:65], v[116:117] op_sel_hi:[0,1,1]
	v_cvt_pk_bf16_f32 v142, v141, v141
	v_pk_fma_f32 v[84:85], v[0:1], v[54:55], v[114:115] op_sel_hi:[0,1,1]
	global_store_short v149, v142, s[100:101]
	v_pk_fma_f32 v[118:119], v[140:141], v[58:59], v[118:119] op_sel_hi:[0,1,1]
	v_pk_fma_f32 v[86:87], v[0:1], v[56:57], v[116:117] op_sel_hi:[0,1,1]
	v_pk_fma_f32 v[120:121], v[140:141], v[60:61], v[120:121] op_sel_hi:[0,1,1]
	v_pk_fma_f32 v[88:89], v[0:1], v[42:43], v[118:119] op_sel_hi:[0,1,1]
	v_pk_fma_f32 v[90:91], v[0:1], v[44:45], v[120:121] op_sel_hi:[0,1,1]
	s_waitcnt lgkmcnt(0)
	v_pk_fma_f32 v[106:107], v[84:85], v[34:35], 0 op_sel_hi:[1,1,0]
	v_pk_fma_f32 v[108:109], v[84:85], v[22:23], 0 op_sel_hi:[1,1,0]
	ds_read_b128 v[70:73], v100 offset:36064
	ds_read_b128 v[66:69], v100 offset:36080
	v_pk_fma_f32 v[106:107], v[86:87], v[36:37], v[106:107]
	v_pk_fma_f32 v[108:109], v[86:87], v[24:25], v[108:109]
	ds_read_b128 v[50:53], v100 offset:36320
	ds_read_b128 v[46:49], v100 offset:36336
	v_pk_fma_f32 v[106:107], v[88:89], v[38:39], v[106:107]
	v_pk_fma_f32 v[108:109], v[88:89], v[18:19], v[108:109]
	ds_read_b128 v[54:57], v100 offset:36576
	ds_read_b128 v[42:45], v100 offset:36592
	v_pk_fma_f32 v[106:107], v[90:91], v[40:41], v[106:107]
	v_pk_fma_f32 v[108:109], v[90:91], v[20:21], v[108:109]
	ds_read_b128 v[78:81], v100 offset:36832
	ds_read_b128 v[74:77], v100 offset:36848
	v_add_f32_e32 v130, v106, v107
	v_add_f32_e32 v131, v108, v109
	v_pk_mul_f32 v[114:115], v[84:85], v[2:3]
	v_add_f32_dpp v130, v130, v130 quad_perm:[1,0,3,2] row_mask:0xf bank_mask:0xf bound_ctrl:1
	v_add_f32_dpp v131, v131, v131 quad_perm:[1,0,3,2] row_mask:0xf bank_mask:0xf bound_ctrl:1
	v_pk_mul_f32 v[116:117], v[86:87], v[4:5]
	v_add_f32_dpp v130, v130, v130 quad_perm:[2,3,0,1] row_mask:0xf bank_mask:0xf bound_ctrl:1
	v_add_f32_dpp v131, v131, v131 quad_perm:[2,3,0,1] row_mask:0xf bank_mask:0xf bound_ctrl:1
	v_pk_mul_f32 v[118:119], v[88:89], v[6:7]
	v_add_f32_dpp v130, v130, v130 row_half_mirror row_mask:0xf bank_mask:0xf bound_ctrl:1
	v_add_f32_dpp v131, v131, v131 row_half_mirror row_mask:0xf bank_mask:0xf bound_ctrl:1
	v_pk_mul_f32 v[120:121], v[90:91], v[8:9]
	ds_read_b128 v[62:65], v100 offset:37088
	ds_read_b128 v[58:61], v100 offset:37104
	v_mul_f32_e32 v132, v130, v96
	v_mul_f32_e32 v133, v97, v94
	ds_read_b32 v0, v101 offset:37344
	v_add_f32_e32 v131, v132, v131
	ds_read_b64 v[98:99], v1 offset:37600
	v_add_f32_e32 v131, v133, v131
	v_pk_fma_f32 v[114:115], v[130:131], v[26:27], v[114:115] op_sel_hi:[0,1,1]
	v_pk_fma_f32 v[116:117], v[130:131], v[28:29], v[116:117] op_sel_hi:[0,1,1]
	v_cvt_pk_bf16_f32 v132, v131, v131
	v_pk_fma_f32 v[84:85], v[94:95], v[10:11], v[114:115] op_sel_hi:[0,1,1]
	global_store_short v150, v132, s[100:101]
	v_pk_fma_f32 v[118:119], v[130:131], v[30:31], v[118:119] op_sel_hi:[0,1,1]
	v_pk_fma_f32 v[86:87], v[94:95], v[12:13], v[116:117] op_sel_hi:[0,1,1]
	v_pk_fma_f32 v[120:121], v[130:131], v[32:33], v[120:121] op_sel_hi:[0,1,1]
	v_pk_fma_f32 v[88:89], v[94:95], v[14:15], v[118:119] op_sel_hi:[0,1,1]
	v_pk_fma_f32 v[90:91], v[94:95], v[16:17], v[120:121] op_sel_hi:[0,1,1]
	s_waitcnt lgkmcnt(0)
	v_pk_fma_f32 v[110:111], v[84:85], v[78:79], 0 op_sel_hi:[1,1,0]
	v_pk_fma_f32 v[112:113], v[84:85], v[70:71], 0 op_sel_hi:[1,1,0]
	ds_read_b128 v[22:25], v100 offset:37632
	ds_read_b128 v[18:21], v100 offset:37648
	v_pk_fma_f32 v[110:111], v[86:87], v[80:81], v[110:111]
	v_pk_fma_f32 v[112:113], v[86:87], v[72:73], v[112:113]
	ds_read_b128 v[2:5], v100 offset:37888
	ds_read_b128 v[6:9], v100 offset:37904
	v_pk_fma_f32 v[110:111], v[88:89], v[74:75], v[110:111]
	v_pk_fma_f32 v[112:113], v[88:89], v[66:67], v[112:113]
	ds_read_b128 v[10:13], v100 offset:38144
	ds_read_b128 v[14:17], v100 offset:38160
	v_pk_fma_f32 v[110:111], v[90:91], v[76:77], v[110:111]
	v_pk_fma_f32 v[112:113], v[90:91], v[68:69], v[112:113]
	ds_read_b128 v[34:37], v100 offset:38400
	ds_read_b128 v[38:41], v100 offset:38416
	v_add_f32_e32 v140, v110, v111
	v_add_f32_e32 v141, v112, v113
	v_pk_mul_f32 v[114:115], v[84:85], v[50:51]
	v_add_f32_dpp v140, v140, v140 quad_perm:[1,0,3,2] row_mask:0xf bank_mask:0xf bound_ctrl:1
	v_add_f32_dpp v141, v141, v141 quad_perm:[1,0,3,2] row_mask:0xf bank_mask:0xf bound_ctrl:1
	v_pk_mul_f32 v[116:117], v[86:87], v[52:53]
	v_add_f32_dpp v140, v140, v140 quad_perm:[2,3,0,1] row_mask:0xf bank_mask:0xf bound_ctrl:1
	v_add_f32_dpp v141, v141, v141 quad_perm:[2,3,0,1] row_mask:0xf bank_mask:0xf bound_ctrl:1
	v_pk_mul_f32 v[118:119], v[88:89], v[46:47]
	v_add_f32_dpp v140, v140, v140 row_half_mirror row_mask:0xf bank_mask:0xf bound_ctrl:1
	v_add_f32_dpp v141, v141, v141 row_half_mirror row_mask:0xf bank_mask:0xf bound_ctrl:1
	v_pk_mul_f32 v[120:121], v[90:91], v[48:49]
	ds_read_b128 v[26:29], v100 offset:38656
	ds_read_b128 v[30:33], v100 offset:38672
	v_mul_f32_e32 v142, v140, v98
	v_mul_f32_e32 v143, v99, v0
	ds_read_b32 v94, v101 offset:38912
	v_add_f32_e32 v141, v142, v141
	ds_read_b64 v[96:97], v1 offset:39168
	v_add_f32_e32 v141, v143, v141
	v_pk_fma_f32 v[114:115], v[140:141], v[62:63], v[114:115] op_sel_hi:[0,1,1]
	v_pk_fma_f32 v[116:117], v[140:141], v[64:65], v[116:117] op_sel_hi:[0,1,1]
	v_cvt_pk_bf16_f32 v142, v141, v141
	v_pk_fma_f32 v[84:85], v[0:1], v[54:55], v[114:115] op_sel_hi:[0,1,1]
	global_store_short v151, v142, s[100:101]
	v_pk_fma_f32 v[118:119], v[140:141], v[58:59], v[118:119] op_sel_hi:[0,1,1]
	v_pk_fma_f32 v[86:87], v[0:1], v[56:57], v[116:117] op_sel_hi:[0,1,1]
	v_pk_fma_f32 v[120:121], v[140:141], v[60:61], v[120:121] op_sel_hi:[0,1,1]
	v_pk_fma_f32 v[88:89], v[0:1], v[42:43], v[118:119] op_sel_hi:[0,1,1]
	v_pk_fma_f32 v[90:91], v[0:1], v[44:45], v[120:121] op_sel_hi:[0,1,1]
	s_waitcnt lgkmcnt(0)
	v_pk_fma_f32 v[106:107], v[84:85], v[34:35], 0 op_sel_hi:[1,1,0]
	v_pk_fma_f32 v[108:109], v[84:85], v[22:23], 0 op_sel_hi:[1,1,0]
	ds_read_b128 v[70:73], v100 offset:39200
	ds_read_b128 v[66:69], v100 offset:39216
	v_pk_fma_f32 v[106:107], v[86:87], v[36:37], v[106:107]
	v_pk_fma_f32 v[108:109], v[86:87], v[24:25], v[108:109]
	ds_read_b128 v[50:53], v100 offset:39456
	ds_read_b128 v[46:49], v100 offset:39472
	v_pk_fma_f32 v[106:107], v[88:89], v[38:39], v[106:107]
	v_pk_fma_f32 v[108:109], v[88:89], v[18:19], v[108:109]
	ds_read_b128 v[54:57], v100 offset:39712
	ds_read_b128 v[42:45], v100 offset:39728
	v_pk_fma_f32 v[106:107], v[90:91], v[40:41], v[106:107]
	v_pk_fma_f32 v[108:109], v[90:91], v[20:21], v[108:109]
	ds_read_b128 v[78:81], v100 offset:39968
	ds_read_b128 v[74:77], v100 offset:39984
	v_add_f32_e32 v130, v106, v107
	v_add_f32_e32 v131, v108, v109
	v_pk_mul_f32 v[114:115], v[84:85], v[2:3]
	v_add_f32_dpp v130, v130, v130 quad_perm:[1,0,3,2] row_mask:0xf bank_mask:0xf bound_ctrl:1
	v_add_f32_dpp v131, v131, v131 quad_perm:[1,0,3,2] row_mask:0xf bank_mask:0xf bound_ctrl:1
	v_pk_mul_f32 v[116:117], v[86:87], v[4:5]
	v_add_f32_dpp v130, v130, v130 quad_perm:[2,3,0,1] row_mask:0xf bank_mask:0xf bound_ctrl:1
	v_add_f32_dpp v131, v131, v131 quad_perm:[2,3,0,1] row_mask:0xf bank_mask:0xf bound_ctrl:1
	v_pk_mul_f32 v[118:119], v[88:89], v[6:7]
	v_add_f32_dpp v130, v130, v130 row_half_mirror row_mask:0xf bank_mask:0xf bound_ctrl:1
	v_add_f32_dpp v131, v131, v131 row_half_mirror row_mask:0xf bank_mask:0xf bound_ctrl:1
	v_pk_mul_f32 v[120:121], v[90:91], v[8:9]
	ds_read_b128 v[62:65], v100 offset:40224
	ds_read_b128 v[58:61], v100 offset:40240
	v_mul_f32_e32 v132, v130, v96
	v_mul_f32_e32 v133, v97, v94
	ds_read_b32 v0, v101 offset:40480
	v_add_f32_e32 v131, v132, v131
	ds_read_b64 v[98:99], v1 offset:40736
	v_add_f32_e32 v131, v133, v131
	v_pk_fma_f32 v[114:115], v[130:131], v[26:27], v[114:115] op_sel_hi:[0,1,1]
	v_pk_fma_f32 v[116:117], v[130:131], v[28:29], v[116:117] op_sel_hi:[0,1,1]
	v_cvt_pk_bf16_f32 v132, v131, v131
	v_pk_fma_f32 v[84:85], v[94:95], v[10:11], v[114:115] op_sel_hi:[0,1,1]
	global_store_short v152, v132, s[100:101]
	v_pk_fma_f32 v[118:119], v[130:131], v[30:31], v[118:119] op_sel_hi:[0,1,1]
	v_pk_fma_f32 v[86:87], v[94:95], v[12:13], v[116:117] op_sel_hi:[0,1,1]
	v_pk_fma_f32 v[120:121], v[130:131], v[32:33], v[120:121] op_sel_hi:[0,1,1]
	v_pk_fma_f32 v[88:89], v[94:95], v[14:15], v[118:119] op_sel_hi:[0,1,1]
	v_pk_fma_f32 v[90:91], v[94:95], v[16:17], v[120:121] op_sel_hi:[0,1,1]
	s_waitcnt lgkmcnt(0)
	v_pk_fma_f32 v[110:111], v[84:85], v[78:79], 0 op_sel_hi:[1,1,0]
	v_pk_fma_f32 v[112:113], v[84:85], v[70:71], 0 op_sel_hi:[1,1,0]
	ds_read_b128 v[22:25], v100 offset:40768
	ds_read_b128 v[18:21], v100 offset:40784
	v_pk_fma_f32 v[110:111], v[86:87], v[80:81], v[110:111]
	v_pk_fma_f32 v[112:113], v[86:87], v[72:73], v[112:113]
	ds_read_b128 v[2:5], v100 offset:41024
	ds_read_b128 v[6:9], v100 offset:41040
	v_pk_fma_f32 v[110:111], v[88:89], v[74:75], v[110:111]
	v_pk_fma_f32 v[112:113], v[88:89], v[66:67], v[112:113]
	ds_read_b128 v[10:13], v100 offset:41280
	ds_read_b128 v[14:17], v100 offset:41296
	v_pk_fma_f32 v[110:111], v[90:91], v[76:77], v[110:111]
	v_pk_fma_f32 v[112:113], v[90:91], v[68:69], v[112:113]
	ds_read_b128 v[34:37], v100 offset:41536
	ds_read_b128 v[38:41], v100 offset:41552
	v_add_f32_e32 v140, v110, v111
	v_add_f32_e32 v141, v112, v113
	v_pk_mul_f32 v[114:115], v[84:85], v[50:51]
	v_add_f32_dpp v140, v140, v140 quad_perm:[1,0,3,2] row_mask:0xf bank_mask:0xf bound_ctrl:1
	v_add_f32_dpp v141, v141, v141 quad_perm:[1,0,3,2] row_mask:0xf bank_mask:0xf bound_ctrl:1
	v_pk_mul_f32 v[116:117], v[86:87], v[52:53]
	v_add_f32_dpp v140, v140, v140 quad_perm:[2,3,0,1] row_mask:0xf bank_mask:0xf bound_ctrl:1
	v_add_f32_dpp v141, v141, v141 quad_perm:[2,3,0,1] row_mask:0xf bank_mask:0xf bound_ctrl:1
	v_pk_mul_f32 v[118:119], v[88:89], v[46:47]
	v_add_f32_dpp v140, v140, v140 row_half_mirror row_mask:0xf bank_mask:0xf bound_ctrl:1
	v_add_f32_dpp v141, v141, v141 row_half_mirror row_mask:0xf bank_mask:0xf bound_ctrl:1
	v_pk_mul_f32 v[120:121], v[90:91], v[48:49]
	ds_read_b128 v[26:29], v100 offset:41792
	ds_read_b128 v[30:33], v100 offset:41808
	v_mul_f32_e32 v142, v140, v98
	v_mul_f32_e32 v143, v99, v0
	ds_read_b32 v94, v101 offset:42048
	v_add_f32_e32 v141, v142, v141
	ds_read_b64 v[96:97], v1 offset:42304
	v_add_f32_e32 v141, v143, v141
	v_pk_fma_f32 v[114:115], v[140:141], v[62:63], v[114:115] op_sel_hi:[0,1,1]
	v_pk_fma_f32 v[116:117], v[140:141], v[64:65], v[116:117] op_sel_hi:[0,1,1]
	v_cvt_pk_bf16_f32 v142, v141, v141
	v_pk_fma_f32 v[84:85], v[0:1], v[54:55], v[114:115] op_sel_hi:[0,1,1]
	global_store_short v153, v142, s[100:101]
	v_pk_fma_f32 v[118:119], v[140:141], v[58:59], v[118:119] op_sel_hi:[0,1,1]
	v_pk_fma_f32 v[86:87], v[0:1], v[56:57], v[116:117] op_sel_hi:[0,1,1]
	v_pk_fma_f32 v[120:121], v[140:141], v[60:61], v[120:121] op_sel_hi:[0,1,1]
	v_pk_fma_f32 v[88:89], v[0:1], v[42:43], v[118:119] op_sel_hi:[0,1,1]
	v_pk_fma_f32 v[90:91], v[0:1], v[44:45], v[120:121] op_sel_hi:[0,1,1]
	s_waitcnt lgkmcnt(0)
	v_pk_fma_f32 v[106:107], v[84:85], v[34:35], 0 op_sel_hi:[1,1,0]
	v_pk_fma_f32 v[108:109], v[84:85], v[22:23], 0 op_sel_hi:[1,1,0]
	ds_read_b128 v[70:73], v100 offset:42336
	ds_read_b128 v[66:69], v100 offset:42352
	v_pk_fma_f32 v[106:107], v[86:87], v[36:37], v[106:107]
	v_pk_fma_f32 v[108:109], v[86:87], v[24:25], v[108:109]
	ds_read_b128 v[50:53], v100 offset:42592
	ds_read_b128 v[46:49], v100 offset:42608
	v_pk_fma_f32 v[106:107], v[88:89], v[38:39], v[106:107]
	v_pk_fma_f32 v[108:109], v[88:89], v[18:19], v[108:109]
	ds_read_b128 v[54:57], v100 offset:42848
	ds_read_b128 v[42:45], v100 offset:42864
	v_pk_fma_f32 v[106:107], v[90:91], v[40:41], v[106:107]
	v_pk_fma_f32 v[108:109], v[90:91], v[20:21], v[108:109]
	ds_read_b128 v[78:81], v100 offset:43104
	ds_read_b128 v[74:77], v100 offset:43120
	v_add_f32_e32 v130, v106, v107
	v_add_f32_e32 v131, v108, v109
	v_pk_mul_f32 v[114:115], v[84:85], v[2:3]
	v_add_f32_dpp v130, v130, v130 quad_perm:[1,0,3,2] row_mask:0xf bank_mask:0xf bound_ctrl:1
	v_add_f32_dpp v131, v131, v131 quad_perm:[1,0,3,2] row_mask:0xf bank_mask:0xf bound_ctrl:1
	v_pk_mul_f32 v[116:117], v[86:87], v[4:5]
	v_add_f32_dpp v130, v130, v130 quad_perm:[2,3,0,1] row_mask:0xf bank_mask:0xf bound_ctrl:1
	v_add_f32_dpp v131, v131, v131 quad_perm:[2,3,0,1] row_mask:0xf bank_mask:0xf bound_ctrl:1
	v_pk_mul_f32 v[118:119], v[88:89], v[6:7]
	v_add_f32_dpp v130, v130, v130 row_half_mirror row_mask:0xf bank_mask:0xf bound_ctrl:1
	v_add_f32_dpp v131, v131, v131 row_half_mirror row_mask:0xf bank_mask:0xf bound_ctrl:1
	v_pk_mul_f32 v[120:121], v[90:91], v[8:9]
	ds_read_b128 v[62:65], v100 offset:43360
	ds_read_b128 v[58:61], v100 offset:43376
	v_mul_f32_e32 v132, v130, v96
	v_mul_f32_e32 v133, v97, v94
	ds_read_b32 v0, v101 offset:43616
	v_add_f32_e32 v131, v132, v131
	ds_read_b64 v[98:99], v1 offset:43872
	v_add_f32_e32 v131, v133, v131
	v_pk_fma_f32 v[114:115], v[130:131], v[26:27], v[114:115] op_sel_hi:[0,1,1]
	v_pk_fma_f32 v[116:117], v[130:131], v[28:29], v[116:117] op_sel_hi:[0,1,1]
	v_cvt_pk_bf16_f32 v132, v131, v131
	v_pk_fma_f32 v[84:85], v[94:95], v[10:11], v[114:115] op_sel_hi:[0,1,1]
	global_store_short v154, v132, s[100:101]
	v_pk_fma_f32 v[118:119], v[130:131], v[30:31], v[118:119] op_sel_hi:[0,1,1]
	v_pk_fma_f32 v[86:87], v[94:95], v[12:13], v[116:117] op_sel_hi:[0,1,1]
	v_pk_fma_f32 v[120:121], v[130:131], v[32:33], v[120:121] op_sel_hi:[0,1,1]
	v_pk_fma_f32 v[88:89], v[94:95], v[14:15], v[118:119] op_sel_hi:[0,1,1]
	v_pk_fma_f32 v[90:91], v[94:95], v[16:17], v[120:121] op_sel_hi:[0,1,1]
	s_waitcnt lgkmcnt(0)
	v_pk_fma_f32 v[110:111], v[84:85], v[78:79], 0 op_sel_hi:[1,1,0]
	v_pk_fma_f32 v[112:113], v[84:85], v[70:71], 0 op_sel_hi:[1,1,0]
	ds_read_b128 v[22:25], v100 offset:43904
	ds_read_b128 v[18:21], v100 offset:43920
	v_pk_fma_f32 v[110:111], v[86:87], v[80:81], v[110:111]
	v_pk_fma_f32 v[112:113], v[86:87], v[72:73], v[112:113]
	ds_read_b128 v[2:5], v100 offset:44160
	ds_read_b128 v[6:9], v100 offset:44176
	v_pk_fma_f32 v[110:111], v[88:89], v[74:75], v[110:111]
	v_pk_fma_f32 v[112:113], v[88:89], v[66:67], v[112:113]
	ds_read_b128 v[10:13], v100 offset:44416
	ds_read_b128 v[14:17], v100 offset:44432
	v_pk_fma_f32 v[110:111], v[90:91], v[76:77], v[110:111]
	v_pk_fma_f32 v[112:113], v[90:91], v[68:69], v[112:113]
	ds_read_b128 v[34:37], v100 offset:44672
	ds_read_b128 v[38:41], v100 offset:44688
	v_add_f32_e32 v140, v110, v111
	v_add_f32_e32 v141, v112, v113
	v_pk_mul_f32 v[114:115], v[84:85], v[50:51]
	v_add_f32_dpp v140, v140, v140 quad_perm:[1,0,3,2] row_mask:0xf bank_mask:0xf bound_ctrl:1
	v_add_f32_dpp v141, v141, v141 quad_perm:[1,0,3,2] row_mask:0xf bank_mask:0xf bound_ctrl:1
	v_pk_mul_f32 v[116:117], v[86:87], v[52:53]
	v_add_f32_dpp v140, v140, v140 quad_perm:[2,3,0,1] row_mask:0xf bank_mask:0xf bound_ctrl:1
	v_add_f32_dpp v141, v141, v141 quad_perm:[2,3,0,1] row_mask:0xf bank_mask:0xf bound_ctrl:1
	v_pk_mul_f32 v[118:119], v[88:89], v[46:47]
	v_add_f32_dpp v140, v140, v140 row_half_mirror row_mask:0xf bank_mask:0xf bound_ctrl:1
	v_add_f32_dpp v141, v141, v141 row_half_mirror row_mask:0xf bank_mask:0xf bound_ctrl:1
	v_pk_mul_f32 v[120:121], v[90:91], v[48:49]
	ds_read_b128 v[26:29], v100 offset:44928
	ds_read_b128 v[30:33], v100 offset:44944
	v_mul_f32_e32 v142, v140, v98
	v_mul_f32_e32 v143, v99, v0
	ds_read_b32 v94, v101 offset:45184
	v_add_f32_e32 v141, v142, v141
	ds_read_b64 v[96:97], v1 offset:45440
	v_add_f32_e32 v141, v143, v141
	v_pk_fma_f32 v[114:115], v[140:141], v[62:63], v[114:115] op_sel_hi:[0,1,1]
	v_pk_fma_f32 v[116:117], v[140:141], v[64:65], v[116:117] op_sel_hi:[0,1,1]
	v_cvt_pk_bf16_f32 v142, v141, v141
	v_pk_fma_f32 v[84:85], v[0:1], v[54:55], v[114:115] op_sel_hi:[0,1,1]
	global_store_short v155, v142, s[100:101]
	v_pk_fma_f32 v[118:119], v[140:141], v[58:59], v[118:119] op_sel_hi:[0,1,1]
	v_pk_fma_f32 v[86:87], v[0:1], v[56:57], v[116:117] op_sel_hi:[0,1,1]
	v_pk_fma_f32 v[120:121], v[140:141], v[60:61], v[120:121] op_sel_hi:[0,1,1]
	v_pk_fma_f32 v[88:89], v[0:1], v[42:43], v[118:119] op_sel_hi:[0,1,1]
	v_pk_fma_f32 v[90:91], v[0:1], v[44:45], v[120:121] op_sel_hi:[0,1,1]
	s_waitcnt lgkmcnt(0)
	v_pk_fma_f32 v[106:107], v[84:85], v[34:35], 0 op_sel_hi:[1,1,0]
	v_pk_fma_f32 v[108:109], v[84:85], v[22:23], 0 op_sel_hi:[1,1,0]
	ds_read_b128 v[70:73], v100 offset:45472
	ds_read_b128 v[66:69], v100 offset:45488
	v_pk_fma_f32 v[106:107], v[86:87], v[36:37], v[106:107]
	v_pk_fma_f32 v[108:109], v[86:87], v[24:25], v[108:109]
	ds_read_b128 v[50:53], v100 offset:45728
	ds_read_b128 v[46:49], v100 offset:45744
	v_pk_fma_f32 v[106:107], v[88:89], v[38:39], v[106:107]
	v_pk_fma_f32 v[108:109], v[88:89], v[18:19], v[108:109]
	ds_read_b128 v[54:57], v100 offset:45984
	ds_read_b128 v[42:45], v100 offset:46000
	v_pk_fma_f32 v[106:107], v[90:91], v[40:41], v[106:107]
	v_pk_fma_f32 v[108:109], v[90:91], v[20:21], v[108:109]
	ds_read_b128 v[78:81], v100 offset:46240
	ds_read_b128 v[74:77], v100 offset:46256
	v_add_f32_e32 v130, v106, v107
	v_add_f32_e32 v131, v108, v109
	v_pk_mul_f32 v[114:115], v[84:85], v[2:3]
	v_add_f32_dpp v130, v130, v130 quad_perm:[1,0,3,2] row_mask:0xf bank_mask:0xf bound_ctrl:1
	v_add_f32_dpp v131, v131, v131 quad_perm:[1,0,3,2] row_mask:0xf bank_mask:0xf bound_ctrl:1
	v_pk_mul_f32 v[116:117], v[86:87], v[4:5]
	v_add_f32_dpp v130, v130, v130 quad_perm:[2,3,0,1] row_mask:0xf bank_mask:0xf bound_ctrl:1
	v_add_f32_dpp v131, v131, v131 quad_perm:[2,3,0,1] row_mask:0xf bank_mask:0xf bound_ctrl:1
	v_pk_mul_f32 v[118:119], v[88:89], v[6:7]
	v_add_f32_dpp v130, v130, v130 row_half_mirror row_mask:0xf bank_mask:0xf bound_ctrl:1
	v_add_f32_dpp v131, v131, v131 row_half_mirror row_mask:0xf bank_mask:0xf bound_ctrl:1
	v_pk_mul_f32 v[120:121], v[90:91], v[8:9]
	ds_read_b128 v[62:65], v100 offset:46496
	ds_read_b128 v[58:61], v100 offset:46512
	v_mul_f32_e32 v132, v130, v96
	v_mul_f32_e32 v133, v97, v94
	ds_read_b32 v0, v101 offset:46752
	v_add_f32_e32 v131, v132, v131
	ds_read_b64 v[98:99], v1 offset:47008
	v_add_f32_e32 v131, v133, v131
	v_pk_fma_f32 v[114:115], v[130:131], v[26:27], v[114:115] op_sel_hi:[0,1,1]
	v_pk_fma_f32 v[116:117], v[130:131], v[28:29], v[116:117] op_sel_hi:[0,1,1]
	v_cvt_pk_bf16_f32 v132, v131, v131
	v_pk_fma_f32 v[84:85], v[94:95], v[10:11], v[114:115] op_sel_hi:[0,1,1]
	global_store_short v156, v132, s[100:101]
	v_pk_fma_f32 v[118:119], v[130:131], v[30:31], v[118:119] op_sel_hi:[0,1,1]
	v_pk_fma_f32 v[86:87], v[94:95], v[12:13], v[116:117] op_sel_hi:[0,1,1]
	v_pk_fma_f32 v[120:121], v[130:131], v[32:33], v[120:121] op_sel_hi:[0,1,1]
	v_pk_fma_f32 v[88:89], v[94:95], v[14:15], v[118:119] op_sel_hi:[0,1,1]
	v_pk_fma_f32 v[90:91], v[94:95], v[16:17], v[120:121] op_sel_hi:[0,1,1]
	s_waitcnt lgkmcnt(0)
	v_pk_fma_f32 v[110:111], v[84:85], v[78:79], 0 op_sel_hi:[1,1,0]
	v_pk_fma_f32 v[112:113], v[84:85], v[70:71], 0 op_sel_hi:[1,1,0]
	ds_read_b128 v[22:25], v100 offset:47040
	ds_read_b128 v[18:21], v100 offset:47056
	v_pk_fma_f32 v[110:111], v[86:87], v[80:81], v[110:111]
	v_pk_fma_f32 v[112:113], v[86:87], v[72:73], v[112:113]
	ds_read_b128 v[2:5], v100 offset:47296
	ds_read_b128 v[6:9], v100 offset:47312
	v_pk_fma_f32 v[110:111], v[88:89], v[74:75], v[110:111]
	v_pk_fma_f32 v[112:113], v[88:89], v[66:67], v[112:113]
	ds_read_b128 v[10:13], v100 offset:47552
	ds_read_b128 v[14:17], v100 offset:47568
	v_pk_fma_f32 v[110:111], v[90:91], v[76:77], v[110:111]
	v_pk_fma_f32 v[112:113], v[90:91], v[68:69], v[112:113]
	ds_read_b128 v[34:37], v100 offset:47808
	ds_read_b128 v[38:41], v100 offset:47824
	v_add_f32_e32 v140, v110, v111
	v_add_f32_e32 v141, v112, v113
	v_pk_mul_f32 v[114:115], v[84:85], v[50:51]
	v_add_f32_dpp v140, v140, v140 quad_perm:[1,0,3,2] row_mask:0xf bank_mask:0xf bound_ctrl:1
	v_add_f32_dpp v141, v141, v141 quad_perm:[1,0,3,2] row_mask:0xf bank_mask:0xf bound_ctrl:1
	v_pk_mul_f32 v[116:117], v[86:87], v[52:53]
	v_add_f32_dpp v140, v140, v140 quad_perm:[2,3,0,1] row_mask:0xf bank_mask:0xf bound_ctrl:1
	v_add_f32_dpp v141, v141, v141 quad_perm:[2,3,0,1] row_mask:0xf bank_mask:0xf bound_ctrl:1
	v_pk_mul_f32 v[118:119], v[88:89], v[46:47]
	v_add_f32_dpp v140, v140, v140 row_half_mirror row_mask:0xf bank_mask:0xf bound_ctrl:1
	v_add_f32_dpp v141, v141, v141 row_half_mirror row_mask:0xf bank_mask:0xf bound_ctrl:1
	v_pk_mul_f32 v[120:121], v[90:91], v[48:49]
	ds_read_b128 v[26:29], v100 offset:48064
	ds_read_b128 v[30:33], v100 offset:48080
	v_mul_f32_e32 v142, v140, v98
	v_mul_f32_e32 v143, v99, v0
	ds_read_b32 v94, v101 offset:48320
	v_add_f32_e32 v141, v142, v141
	ds_read_b64 v[96:97], v1 offset:48576
	v_add_f32_e32 v141, v143, v141
	v_pk_fma_f32 v[114:115], v[140:141], v[62:63], v[114:115] op_sel_hi:[0,1,1]
	v_pk_fma_f32 v[116:117], v[140:141], v[64:65], v[116:117] op_sel_hi:[0,1,1]
	v_cvt_pk_bf16_f32 v142, v141, v141
	v_pk_fma_f32 v[84:85], v[0:1], v[54:55], v[114:115] op_sel_hi:[0,1,1]
	global_store_short v157, v142, s[100:101]
	v_pk_fma_f32 v[118:119], v[140:141], v[58:59], v[118:119] op_sel_hi:[0,1,1]
	v_pk_fma_f32 v[86:87], v[0:1], v[56:57], v[116:117] op_sel_hi:[0,1,1]
	v_pk_fma_f32 v[120:121], v[140:141], v[60:61], v[120:121] op_sel_hi:[0,1,1]
	v_pk_fma_f32 v[88:89], v[0:1], v[42:43], v[118:119] op_sel_hi:[0,1,1]
	v_pk_fma_f32 v[90:91], v[0:1], v[44:45], v[120:121] op_sel_hi:[0,1,1]
	s_waitcnt lgkmcnt(0)
	v_pk_fma_f32 v[106:107], v[84:85], v[34:35], 0 op_sel_hi:[1,1,0]
	v_pk_fma_f32 v[108:109], v[84:85], v[22:23], 0 op_sel_hi:[1,1,0]
	ds_read_b128 v[70:73], v100 offset:48608
	ds_read_b128 v[66:69], v100 offset:48624
	v_pk_fma_f32 v[106:107], v[86:87], v[36:37], v[106:107]
	v_pk_fma_f32 v[108:109], v[86:87], v[24:25], v[108:109]
	ds_read_b128 v[50:53], v100 offset:48864
	ds_read_b128 v[46:49], v100 offset:48880
	v_pk_fma_f32 v[106:107], v[88:89], v[38:39], v[106:107]
	v_pk_fma_f32 v[108:109], v[88:89], v[18:19], v[108:109]
	ds_read_b128 v[54:57], v100 offset:49120
	ds_read_b128 v[42:45], v100 offset:49136
	v_pk_fma_f32 v[106:107], v[90:91], v[40:41], v[106:107]
	v_pk_fma_f32 v[108:109], v[90:91], v[20:21], v[108:109]
	ds_read_b128 v[78:81], v100 offset:49376
	ds_read_b128 v[74:77], v100 offset:49392
	v_add_f32_e32 v130, v106, v107
	v_add_f32_e32 v131, v108, v109
	v_pk_mul_f32 v[114:115], v[84:85], v[2:3]
	v_add_f32_dpp v130, v130, v130 quad_perm:[1,0,3,2] row_mask:0xf bank_mask:0xf bound_ctrl:1
	v_add_f32_dpp v131, v131, v131 quad_perm:[1,0,3,2] row_mask:0xf bank_mask:0xf bound_ctrl:1
	v_pk_mul_f32 v[116:117], v[86:87], v[4:5]
	v_add_f32_dpp v130, v130, v130 quad_perm:[2,3,0,1] row_mask:0xf bank_mask:0xf bound_ctrl:1
	v_add_f32_dpp v131, v131, v131 quad_perm:[2,3,0,1] row_mask:0xf bank_mask:0xf bound_ctrl:1
	v_pk_mul_f32 v[118:119], v[88:89], v[6:7]
	v_add_f32_dpp v130, v130, v130 row_half_mirror row_mask:0xf bank_mask:0xf bound_ctrl:1
	v_add_f32_dpp v131, v131, v131 row_half_mirror row_mask:0xf bank_mask:0xf bound_ctrl:1
	v_pk_mul_f32 v[120:121], v[90:91], v[8:9]
	ds_read_b128 v[62:65], v100 offset:49632
	ds_read_b128 v[58:61], v100 offset:49648
	v_mul_f32_e32 v132, v130, v96
	v_mul_f32_e32 v133, v97, v94
	ds_read_b32 v0, v101 offset:49888
	v_add_f32_e32 v131, v132, v131
	ds_read_b64 v[98:99], v1 offset:50144
	v_add_f32_e32 v131, v133, v131
	v_pk_fma_f32 v[114:115], v[130:131], v[26:27], v[114:115] op_sel_hi:[0,1,1]
	v_pk_fma_f32 v[116:117], v[130:131], v[28:29], v[116:117] op_sel_hi:[0,1,1]
	v_cvt_pk_bf16_f32 v132, v131, v131
	v_pk_fma_f32 v[84:85], v[94:95], v[10:11], v[114:115] op_sel_hi:[0,1,1]
	global_store_short v158, v132, s[100:101]
	v_pk_fma_f32 v[118:119], v[130:131], v[30:31], v[118:119] op_sel_hi:[0,1,1]
	v_pk_fma_f32 v[86:87], v[94:95], v[12:13], v[116:117] op_sel_hi:[0,1,1]
	v_pk_fma_f32 v[120:121], v[130:131], v[32:33], v[120:121] op_sel_hi:[0,1,1]
	v_pk_fma_f32 v[88:89], v[94:95], v[14:15], v[118:119] op_sel_hi:[0,1,1]
	v_pk_fma_f32 v[90:91], v[94:95], v[16:17], v[120:121] op_sel_hi:[0,1,1]
	s_waitcnt lgkmcnt(0)
	v_pk_fma_f32 v[110:111], v[84:85], v[78:79], 0 op_sel_hi:[1,1,0]
	v_pk_fma_f32 v[112:113], v[84:85], v[70:71], 0 op_sel_hi:[1,1,0]
	v_pk_fma_f32 v[110:111], v[86:87], v[80:81], v[110:111]
	v_pk_fma_f32 v[112:113], v[86:87], v[72:73], v[112:113]
	v_pk_fma_f32 v[110:111], v[88:89], v[74:75], v[110:111]
	v_pk_fma_f32 v[112:113], v[88:89], v[66:67], v[112:113]
	v_pk_fma_f32 v[110:111], v[90:91], v[76:77], v[110:111]
	v_pk_fma_f32 v[112:113], v[90:91], v[68:69], v[112:113]
	v_add_f32_e32 v140, v110, v111
	v_add_f32_e32 v141, v112, v113
	v_pk_mul_f32 v[114:115], v[84:85], v[50:51]
	v_add_f32_dpp v140, v140, v140 quad_perm:[1,0,3,2] row_mask:0xf bank_mask:0xf bound_ctrl:1
	v_add_f32_dpp v141, v141, v141 quad_perm:[1,0,3,2] row_mask:0xf bank_mask:0xf bound_ctrl:1
	v_pk_mul_f32 v[116:117], v[86:87], v[52:53]
	v_add_f32_dpp v140, v140, v140 quad_perm:[2,3,0,1] row_mask:0xf bank_mask:0xf bound_ctrl:1
	v_add_f32_dpp v141, v141, v141 quad_perm:[2,3,0,1] row_mask:0xf bank_mask:0xf bound_ctrl:1
	v_pk_mul_f32 v[118:119], v[88:89], v[46:47]
	v_add_f32_dpp v140, v140, v140 row_half_mirror row_mask:0xf bank_mask:0xf bound_ctrl:1
	v_add_f32_dpp v141, v141, v141 row_half_mirror row_mask:0xf bank_mask:0xf bound_ctrl:1
	v_pk_mul_f32 v[120:121], v[90:91], v[48:49]
	v_mul_f32_e32 v142, v140, v98
	v_mul_f32_e32 v143, v99, v0
	v_add_f32_e32 v141, v142, v141
	v_add_f32_e32 v141, v143, v141
	v_pk_fma_f32 v[114:115], v[140:141], v[62:63], v[114:115] op_sel_hi:[0,1,1]
	v_pk_fma_f32 v[116:117], v[140:141], v[64:65], v[116:117] op_sel_hi:[0,1,1]
	v_cvt_pk_bf16_f32 v142, v141, v141
	v_pk_fma_f32 v[84:85], v[0:1], v[54:55], v[114:115] op_sel_hi:[0,1,1]
	global_store_short v159, v142, s[100:101]
	v_pk_fma_f32 v[118:119], v[140:141], v[58:59], v[118:119] op_sel_hi:[0,1,1]
	v_pk_fma_f32 v[86:87], v[0:1], v[56:57], v[116:117] op_sel_hi:[0,1,1]
	v_pk_fma_f32 v[120:121], v[140:141], v[60:61], v[120:121] op_sel_hi:[0,1,1]
	v_pk_fma_f32 v[88:89], v[0:1], v[42:43], v[118:119] op_sel_hi:[0,1,1]
	v_pk_fma_f32 v[90:91], v[0:1], v[44:45], v[120:121] op_sel_hi:[0,1,1]
	s_branch .LBB0_852
